# stacked further: phase-3 task index prefetched one task ahead; GEMM main-loop global_load_lds take SGPR-base addresses (VALU 64-bit adds removed)
# speedup vs baseline: 1.1159x; 1.0045x over previous
.LBB0_37:
	s_add_i32 s69, s48, 2
	s_add_u32 s46, s0, 0x100
	s_addc_u32 s47, s1, 0
	s_add_i32 s70, 0, 0x10000
	v_add_u32_e32 v156, s70, v153
	ds_read_b128 v[140:143], v156
	ds_read_b128 v[144:147], v156 offset:1024
	ds_read_b128 v[148:151], v156 offset:2048
	ds_read_b128 v[168:171], v156 offset:3072
	s_cmp_eq_u32 s12, s48
	s_cselect_b32 s48, s44, s13
	s_cselect_b32 s51, s43, s47
	s_cselect_b32 s50, s42, s46
	s_cselect_b32 s49, s45, s68
	v_lshl_add_u64 v[156:157], s[0:1], 0, v[136:137]
	s_add_i32 m0, s53, 0xc000
	ds_read_b128 v[172:175], v155
	ds_read_b128 v[176:179], v155 offset:1024
	ds_read_b128 v[180:183], v155 offset:2048
	ds_read_b128 v[184:187], v155 offset:3072
	ds_read_b128 v[188:191], v155 offset:4096
	ds_read_b128 v[192:195], v155 offset:5120
	ds_read_b128 v[196:199], v155 offset:6144
	ds_read_b128 v[224:227], v155 offset:7168
	global_load_lds_dwordx4 v[156:157], off
	v_lshl_add_u64 v[156:157], s[0:1], 0, v[138:139]
	s_add_i32 m0, s53, 0xe000
	s_nop 0
	global_load_lds_dwordx4 v[156:157], off
	s_waitcnt lgkmcnt(8)
	s_barrier
	s_waitcnt lgkmcnt(0)
	s_waitcnt lgkmcnt(0)
	v_mfma_f32_16x16x32_bf16 v[126:129], v[140:143], v[172:175], v[126:129]
	v_mfma_f32_16x16x32_bf16 v[122:125], v[148:151], v[172:175], v[122:125]
	v_mfma_f32_16x16x32_bf16 v[110:113], v[140:143], v[180:183], v[110:113]
	v_mfma_f32_16x16x32_bf16 v[106:109], v[148:151], v[180:183], v[106:109]
	v_mfma_f32_16x16x32_bf16 v[94:97], v[140:143], v[188:191], v[94:97]
	v_mfma_f32_16x16x32_bf16 v[90:93], v[148:151], v[188:191], v[90:93]
	v_mfma_f32_16x16x32_bf16 v[78:81], v[140:143], v[196:199], v[78:81]
	v_mfma_f32_16x16x32_bf16 v[74:77], v[148:151], v[196:199], v[74:77]
	v_mfma_f32_16x16x32_bf16 v[126:129], v[144:147], v[176:179], v[126:129]
	v_mfma_f32_16x16x32_bf16 v[122:125], v[168:171], v[176:179], v[122:125]
	v_mfma_f32_16x16x32_bf16 v[110:113], v[144:147], v[184:187], v[110:113]
	v_mfma_f32_16x16x32_bf16 v[106:109], v[168:171], v[184:187], v[106:109]
	v_mfma_f32_16x16x32_bf16 v[94:97], v[144:147], v[192:195], v[94:97]
	v_mfma_f32_16x16x32_bf16 v[90:93], v[168:171], v[192:195], v[90:93]
	v_mfma_f32_16x16x32_bf16 v[78:81], v[144:147], v[224:227], v[78:81]
	v_mfma_f32_16x16x32_bf16 v[74:77], v[168:171], v[224:227], v[74:77]
	s_barrier
	s_add_i32 s71, 0, 0x14000
	v_add_u32_e32 v156, s71, v153
	s_add_i32 s0, s70, s52
	ds_read_b128 v[228:231], v156
	ds_read_b128 v[232:235], v156 offset:1024
	ds_read_b128 v[236:239], v156 offset:2048
	ds_read_b128 v[240:243], v156 offset:3072
	s_add_u32 s76, s48, s94
	s_addc_u32 s77, s49, s95
	s_mov_b32 m0, s0
	s_nop 0
	global_load_lds_dwordx4 v0, s[48:49]
	s_add_i32 m0, s0, 0x2000
	s_nop 0
	global_load_lds_dwordx4 v130, s[48:49]
	s_barrier
	s_waitcnt lgkmcnt(0)
	s_waitcnt lgkmcnt(0)
	v_mfma_f32_16x16x32_bf16 v[118:121], v[228:231], v[172:175], v[118:121]
	v_mfma_f32_16x16x32_bf16 v[114:117], v[236:239], v[172:175], v[114:117]
	v_mfma_f32_16x16x32_bf16 v[102:105], v[228:231], v[180:183], v[102:105]
	v_mfma_f32_16x16x32_bf16 v[98:101], v[236:239], v[180:183], v[98:101]
	v_mfma_f32_16x16x32_bf16 v[86:89], v[228:231], v[188:191], v[86:89]
	v_mfma_f32_16x16x32_bf16 v[82:85], v[236:239], v[188:191], v[82:85]
	v_mfma_f32_16x16x32_bf16 v[70:73], v[228:231], v[196:199], v[70:73]
	v_mfma_f32_16x16x32_bf16 v[66:69], v[236:239], v[196:199], v[66:69]
	v_mfma_f32_16x16x32_bf16 v[118:121], v[232:235], v[176:179], v[118:121]
	v_mfma_f32_16x16x32_bf16 v[114:117], v[240:243], v[176:179], v[114:117]
	v_mfma_f32_16x16x32_bf16 v[102:105], v[232:235], v[184:187], v[102:105]
	v_mfma_f32_16x16x32_bf16 v[98:101], v[240:243], v[184:187], v[98:101]
	v_mfma_f32_16x16x32_bf16 v[86:89], v[232:235], v[192:195], v[86:89]
	v_mfma_f32_16x16x32_bf16 v[82:85], v[240:243], v[192:195], v[82:85]
	v_mfma_f32_16x16x32_bf16 v[70:73], v[232:235], v[224:227], v[70:73]
	v_mfma_f32_16x16x32_bf16 v[66:69], v[240:243], v[224:227], v[66:69]
	s_mov_b32 m0, s53
	s_add_u32 s78, s50, s94
	s_addc_u32 s79, s51, s95
	s_barrier
	ds_read_b128 v[172:175], v155 offset:16384
	ds_read_b128 v[176:179], v155 offset:17408
	ds_read_b128 v[180:183], v155 offset:18432
	ds_read_b128 v[184:187], v155 offset:19456
	ds_read_b128 v[188:191], v155 offset:20480
	ds_read_b128 v[192:195], v155 offset:21504
	ds_read_b128 v[196:199], v155 offset:22528
	ds_read_b128 v[224:227], v155 offset:23552
	global_load_lds_dwordx4 v134, s[50:51]
	s_mov_b32 m0, s54
	s_nop 0
	global_load_lds_dwordx4 v132, s[50:51]
	s_barrier
	s_waitcnt lgkmcnt(0)
	s_waitcnt lgkmcnt(0)
	v_mfma_f32_16x16x32_bf16 v[62:65], v[140:143], v[172:175], v[62:65]
	v_mfma_f32_16x16x32_bf16 v[58:61], v[148:151], v[172:175], v[58:61]
	v_mfma_f32_16x16x32_bf16 v[46:49], v[140:143], v[180:183], v[46:49]
	v_mfma_f32_16x16x32_bf16 v[42:45], v[148:151], v[180:183], v[42:45]
	v_mfma_f32_16x16x32_bf16 v[30:33], v[140:143], v[188:191], v[30:33]
	v_mfma_f32_16x16x32_bf16 v[26:29], v[148:151], v[188:191], v[26:29]
	v_mfma_f32_16x16x32_bf16 v[14:17], v[140:143], v[196:199], v[14:17]
	v_mfma_f32_16x16x32_bf16 v[10:13], v[148:151], v[196:199], v[10:13]
	v_mfma_f32_16x16x32_bf16 v[62:65], v[144:147], v[176:179], v[62:65]
	v_mfma_f32_16x16x32_bf16 v[58:61], v[168:171], v[176:179], v[58:61]
	v_mfma_f32_16x16x32_bf16 v[46:49], v[144:147], v[184:187], v[46:49]
	v_mfma_f32_16x16x32_bf16 v[42:45], v[168:171], v[184:187], v[42:45]
	v_mfma_f32_16x16x32_bf16 v[30:33], v[144:147], v[192:195], v[30:33]
	v_mfma_f32_16x16x32_bf16 v[26:29], v[168:171], v[192:195], v[26:29]
	v_mfma_f32_16x16x32_bf16 v[14:17], v[144:147], v[224:227], v[14:17]
	v_mfma_f32_16x16x32_bf16 v[10:13], v[168:171], v[224:227], v[10:13]
	s_barrier
	s_add_u32 s0, s48, 0x160000
	s_addc_u32 s1, s49, 0
	s_add_i32 s70, s71, s52
	s_mov_b32 m0, s70
	s_nop 0
	global_load_lds_dwordx4 v0, s[0:1]
	s_add_i32 m0, s70, 0x2000
	s_nop 0
	global_load_lds_dwordx4 v130, s[0:1]
	s_waitcnt vmcnt(6)
	s_barrier
	v_mfma_f32_16x16x32_bf16 v[54:57], v[228:231], v[172:175], v[54:57]
	v_mfma_f32_16x16x32_bf16 v[50:53], v[236:239], v[172:175], v[50:53]
	v_mfma_f32_16x16x32_bf16 v[38:41], v[228:231], v[180:183], v[38:41]
	v_mfma_f32_16x16x32_bf16 v[34:37], v[236:239], v[180:183], v[34:37]
	v_mfma_f32_16x16x32_bf16 v[22:25], v[228:231], v[188:191], v[22:25]
	v_mfma_f32_16x16x32_bf16 v[18:21], v[236:239], v[188:191], v[18:21]
	v_mfma_f32_16x16x32_bf16 v[6:9], v[228:231], v[196:199], v[6:9]
	v_mfma_f32_16x16x32_bf16 v[2:5], v[236:239], v[196:199], v[2:5]
	v_mfma_f32_16x16x32_bf16 v[54:57], v[232:235], v[176:179], v[54:57]
	v_mfma_f32_16x16x32_bf16 v[50:53], v[240:243], v[176:179], v[50:53]
	v_mfma_f32_16x16x32_bf16 v[38:41], v[232:235], v[184:187], v[38:41]
	v_mfma_f32_16x16x32_bf16 v[34:37], v[240:243], v[184:187], v[34:37]
	v_mfma_f32_16x16x32_bf16 v[22:25], v[232:235], v[192:195], v[22:25]
	v_mfma_f32_16x16x32_bf16 v[18:21], v[240:243], v[192:195], v[18:21]
	v_mfma_f32_16x16x32_bf16 v[6:9], v[232:235], v[224:227], v[6:9]
	v_mfma_f32_16x16x32_bf16 v[2:5], v[240:243], v[224:227], v[2:5]
	s_add_i32 s70, 0, 0x18000
	v_add_u32_e32 v161, s70, v153
	s_barrier
	ds_read_b128 v[140:143], v161
	ds_read_b128 v[144:147], v161 offset:1024
	ds_read_b128 v[148:151], v161 offset:2048
	ds_read_b128 v[168:171], v161 offset:3072
	s_add_u32 s0, s50, 0x2c0000
	s_addc_u32 s1, s51, 0
	s_mov_b32 m0, s55
	ds_read_b128 v[172:175], v155 offset:32768
	ds_read_b128 v[176:179], v155 offset:33792
	ds_read_b128 v[180:183], v155 offset:34816
	ds_read_b128 v[184:187], v155 offset:35840
	ds_read_b128 v[188:191], v155 offset:36864
	ds_read_b128 v[192:195], v155 offset:37888
	ds_read_b128 v[196:199], v155 offset:38912
	ds_read_b128 v[224:227], v155 offset:39936
	global_load_lds_dwordx4 v134, s[0:1]
	s_mov_b32 m0, s56
	s_nop 0
	global_load_lds_dwordx4 v132, s[0:1]
	s_waitcnt lgkmcnt(8)
	s_barrier
	s_waitcnt lgkmcnt(0)
	s_waitcnt lgkmcnt(0)
	v_mfma_f32_16x16x32_bf16 v[126:129], v[140:143], v[172:175], v[126:129]
	v_mfma_f32_16x16x32_bf16 v[122:125], v[148:151], v[172:175], v[122:125]
	v_mfma_f32_16x16x32_bf16 v[110:113], v[140:143], v[180:183], v[110:113]
	v_mfma_f32_16x16x32_bf16 v[106:109], v[148:151], v[180:183], v[106:109]
	v_mfma_f32_16x16x32_bf16 v[94:97], v[140:143], v[188:191], v[94:97]
	v_mfma_f32_16x16x32_bf16 v[90:93], v[148:151], v[188:191], v[90:93]
	v_mfma_f32_16x16x32_bf16 v[78:81], v[140:143], v[196:199], v[78:81]
	v_mfma_f32_16x16x32_bf16 v[74:77], v[148:151], v[196:199], v[74:77]
	v_mfma_f32_16x16x32_bf16 v[126:129], v[144:147], v[176:179], v[126:129]
	v_mfma_f32_16x16x32_bf16 v[122:125], v[168:171], v[176:179], v[122:125]
	v_mfma_f32_16x16x32_bf16 v[110:113], v[144:147], v[184:187], v[110:113]
	v_mfma_f32_16x16x32_bf16 v[106:109], v[168:171], v[184:187], v[106:109]
	v_mfma_f32_16x16x32_bf16 v[94:97], v[144:147], v[192:195], v[94:97]
	v_mfma_f32_16x16x32_bf16 v[90:93], v[168:171], v[192:195], v[90:93]
	v_mfma_f32_16x16x32_bf16 v[78:81], v[144:147], v[224:227], v[78:81]
	v_mfma_f32_16x16x32_bf16 v[74:77], v[168:171], v[224:227], v[74:77]
	s_barrier
	s_add_i32 s50, 0, 0x1c000
	s_add_i32 s0, s70, s52
	v_add_u32_e32 v161, s50, v153
	s_mov_b32 m0, s0
	ds_read_b128 v[228:231], v161
	ds_read_b128 v[232:235], v161 offset:1024
	ds_read_b128 v[236:239], v161 offset:2048
	ds_read_b128 v[240:243], v161 offset:3072
	global_load_lds_dwordx4 v0, s[76:77]
	s_add_i32 m0, s0, 0x2000
	s_nop 0
	global_load_lds_dwordx4 v130, s[76:77]
	s_barrier
	s_waitcnt lgkmcnt(0)
	s_waitcnt lgkmcnt(0)
	v_mfma_f32_16x16x32_bf16 v[118:121], v[228:231], v[172:175], v[118:121]
	v_mfma_f32_16x16x32_bf16 v[114:117], v[236:239], v[172:175], v[114:117]
	v_mfma_f32_16x16x32_bf16 v[102:105], v[228:231], v[180:183], v[102:105]
	v_mfma_f32_16x16x32_bf16 v[98:101], v[236:239], v[180:183], v[98:101]
	v_mfma_f32_16x16x32_bf16 v[86:89], v[228:231], v[188:191], v[86:89]
	v_mfma_f32_16x16x32_bf16 v[82:85], v[236:239], v[188:191], v[82:85]
	v_mfma_f32_16x16x32_bf16 v[70:73], v[228:231], v[196:199], v[70:73]
	v_mfma_f32_16x16x32_bf16 v[66:69], v[236:239], v[196:199], v[66:69]
	v_mfma_f32_16x16x32_bf16 v[118:121], v[232:235], v[176:179], v[118:121]
	v_mfma_f32_16x16x32_bf16 v[114:117], v[240:243], v[176:179], v[114:117]
	v_mfma_f32_16x16x32_bf16 v[102:105], v[232:235], v[184:187], v[102:105]
	v_mfma_f32_16x16x32_bf16 v[98:101], v[240:243], v[184:187], v[98:101]
	v_mfma_f32_16x16x32_bf16 v[86:89], v[232:235], v[192:195], v[86:89]
	v_mfma_f32_16x16x32_bf16 v[82:85], v[240:243], v[192:195], v[82:85]
	v_mfma_f32_16x16x32_bf16 v[70:73], v[232:235], v[224:227], v[70:73]
	v_mfma_f32_16x16x32_bf16 v[66:69], v[240:243], v[224:227], v[66:69]
	s_mov_b32 m0, s57
	s_barrier
	ds_read_b128 v[172:175], v155 offset:49152
	ds_read_b128 v[176:179], v155 offset:50176
	ds_read_b128 v[180:183], v155 offset:51200
	ds_read_b128 v[184:187], v155 offset:52224
	ds_read_b128 v[188:191], v155 offset:53248
	ds_read_b128 v[192:195], v155 offset:54272
	ds_read_b128 v[196:199], v155 offset:55296
	ds_read_b128 v[224:227], v155 offset:56320
	global_load_lds_dwordx4 v134, s[78:79]
	s_mov_b32 m0, s58
	s_nop 0
	global_load_lds_dwordx4 v132, s[78:79]
	s_barrier
	s_waitcnt lgkmcnt(0)
	s_waitcnt lgkmcnt(0)
	v_mfma_f32_16x16x32_bf16 v[62:65], v[140:143], v[172:175], v[62:65]
	v_mfma_f32_16x16x32_bf16 v[58:61], v[148:151], v[172:175], v[58:61]
	v_mfma_f32_16x16x32_bf16 v[46:49], v[140:143], v[180:183], v[46:49]
	v_mfma_f32_16x16x32_bf16 v[42:45], v[148:151], v[180:183], v[42:45]
	v_mfma_f32_16x16x32_bf16 v[30:33], v[140:143], v[188:191], v[30:33]
	v_mfma_f32_16x16x32_bf16 v[26:29], v[148:151], v[188:191], v[26:29]
	v_mfma_f32_16x16x32_bf16 v[14:17], v[140:143], v[196:199], v[14:17]
	v_mfma_f32_16x16x32_bf16 v[10:13], v[148:151], v[196:199], v[10:13]
	v_mfma_f32_16x16x32_bf16 v[62:65], v[144:147], v[176:179], v[62:65]
	v_mfma_f32_16x16x32_bf16 v[58:61], v[168:171], v[176:179], v[58:61]
	v_mfma_f32_16x16x32_bf16 v[46:49], v[144:147], v[184:187], v[46:49]
	v_mfma_f32_16x16x32_bf16 v[42:45], v[168:171], v[184:187], v[42:45]
	v_mfma_f32_16x16x32_bf16 v[30:33], v[144:147], v[192:195], v[30:33]
	v_mfma_f32_16x16x32_bf16 v[26:29], v[168:171], v[192:195], v[26:29]
	v_mfma_f32_16x16x32_bf16 v[14:17], v[144:147], v[224:227], v[14:17]
	v_mfma_f32_16x16x32_bf16 v[10:13], v[168:171], v[224:227], v[10:13]
	s_barrier
	s_add_u32 s0, s48, 0x160080
	s_addc_u32 s1, s49, 0
	s_add_i32 s48, s50, s52
	s_mov_b32 m0, s48
	s_nop 0
	global_load_lds_dwordx4 v0, s[0:1]
	s_add_i32 m0, s48, 0x2000
	s_nop 0
	global_load_lds_dwordx4 v130, s[0:1]
	s_waitcnt vmcnt(6)
	s_barrier
	v_mfma_f32_16x16x32_bf16 v[54:57], v[228:231], v[172:175], v[54:57]
	v_mfma_f32_16x16x32_bf16 v[50:53], v[236:239], v[172:175], v[50:53]
	v_mfma_f32_16x16x32_bf16 v[38:41], v[228:231], v[180:183], v[38:41]
	v_mfma_f32_16x16x32_bf16 v[34:37], v[236:239], v[180:183], v[34:37]
	v_mfma_f32_16x16x32_bf16 v[22:25], v[228:231], v[188:191], v[22:25]
	v_mfma_f32_16x16x32_bf16 v[18:21], v[236:239], v[188:191], v[18:21]
	v_mfma_f32_16x16x32_bf16 v[6:9], v[228:231], v[196:199], v[6:9]
	v_mfma_f32_16x16x32_bf16 v[2:5], v[236:239], v[196:199], v[2:5]
	v_mfma_f32_16x16x32_bf16 v[54:57], v[232:235], v[176:179], v[54:57]
	v_mfma_f32_16x16x32_bf16 v[50:53], v[240:243], v[176:179], v[50:53]
	v_mfma_f32_16x16x32_bf16 v[38:41], v[232:235], v[184:187], v[38:41]
	v_mfma_f32_16x16x32_bf16 v[34:37], v[240:243], v[184:187], v[34:37]
	v_mfma_f32_16x16x32_bf16 v[22:25], v[232:235], v[192:195], v[22:25]
	v_mfma_f32_16x16x32_bf16 v[18:21], v[240:243], v[192:195], v[18:21]
	v_mfma_f32_16x16x32_bf16 v[6:9], v[232:235], v[224:227], v[6:9]
	v_mfma_f32_16x16x32_bf16 v[2:5], v[240:243], v[224:227], v[2:5]
	s_add_u32 s13, s13, 0x100
	s_addc_u32 s68, s68, 0
	s_cmp_ge_i32 s69, s39
	s_mov_b64 s[0:1], s[46:47]
	s_mov_b32 s48, s69
	s_barrier
	s_cbranch_scc0 .LBB0_37
	s_cmp_eq_u32 s65, 2
	s_cbranch_scc1 .Lepi10_orig
	v_readlane_b32 s90, v255, 17
	v_readlane_b32 s91, v255, 18
	v_readlane_b32 s96, v255, 19
	v_readlane_b32 s97, v255, 20
	v_lshl_or_b32 v156, s66, 8, v154
	v_lshlrev_b32_e32 v156, 2, v156
	v_lshl_add_u32 v157, v152, 13, v156
	s_lshl_b32 s72, s67, 21
	s_add_u32 s74, s22, s72
	s_addc_u32 s75, s23, 0
	s_add_u32 s76, s22, s72
	s_addc_u32 s77, s23, 0
	s_lshr_b32 s73, s67, 3
	s_mul_i32 s73, s73, 0xc000
	s_add_u32 s73, s73, 0xa000
	s_add_u32 s70, s90, s73
	s_addc_u32 s71, s91, 0
	global_load_dwordx4 v[140:143], v156, s[70:71]
	global_load_dwordx4 v[144:147], v156, s[70:71] offset:64
	global_load_dwordx4 v[148:151], v156, s[70:71] offset:512
	global_load_dwordx4 v[168:171], v156, s[70:71] offset:576
	global_load_dwordx4 v[224:227], v157, s[74:75] nt
	global_load_dwordx4 v[228:231], v157, s[74:75] offset:64 nt
	global_load_dwordx4 v[232:235], v157, s[74:75] offset:512 nt
	global_load_dwordx4 v[236:239], v157, s[74:75] offset:576 nt
	s_add_u32 s74, s74, 0x20000
	s_addc_u32 s75, s75, 0
	global_load_dwordx4 v[240:243], v157, s[74:75] nt
	global_load_dwordx4 v[244:247], v157, s[74:75] offset:64 nt
	s_waitcnt vmcnt(5)
	v_pk_fma_f32 v[128:129], v[128:129], v[142:143], v[226:227]
	v_pk_fma_f32 v[126:127], v[126:127], v[140:141], v[224:225]
	global_store_dwordx4 v157, v[126:129], s[76:77] nt
	global_load_dwordx4 v[224:227], v157, s[74:75] offset:512 nt
	s_waitcnt vmcnt(6)
	v_pk_fma_f32 v[124:125], v[124:125], v[146:147], v[230:231]
	v_pk_fma_f32 v[122:123], v[122:123], v[144:145], v[228:229]
	global_store_dwordx4 v157, v[122:125], s[76:77] offset:64 nt
	global_load_dwordx4 v[228:231], v157, s[74:75] offset:576 nt
	s_waitcnt vmcnt(7)
	v_pk_fma_f32 v[120:121], v[120:121], v[150:151], v[234:235]
	v_pk_fma_f32 v[118:119], v[118:119], v[148:149], v[232:233]
	global_store_dwordx4 v157, v[118:121], s[76:77] offset:512 nt
	s_add_u32 s74, s74, 0x20000
	s_addc_u32 s75, s75, 0
	global_load_dwordx4 v[232:235], v157, s[74:75] nt
	s_waitcnt vmcnt(8)
	v_pk_fma_f32 v[116:117], v[116:117], v[170:171], v[238:239]
	v_pk_fma_f32 v[114:115], v[114:115], v[168:169], v[236:237]
	global_store_dwordx4 v157, v[114:117], s[76:77] offset:576 nt
	global_load_dwordx4 v[236:239], v157, s[74:75] offset:64 nt
	s_add_u32 s76, s76, 0x20000
	s_addc_u32 s77, s77, 0
	s_waitcnt vmcnt(9)
	v_pk_fma_f32 v[112:113], v[112:113], v[142:143], v[242:243]
	v_pk_fma_f32 v[110:111], v[110:111], v[140:141], v[240:241]
	global_store_dwordx4 v157, v[110:113], s[76:77] nt
	global_load_dwordx4 v[240:243], v157, s[74:75] offset:512 nt
	s_waitcnt vmcnt(10)
	v_pk_fma_f32 v[108:109], v[108:109], v[146:147], v[246:247]
	v_pk_fma_f32 v[106:107], v[106:107], v[144:145], v[244:245]
	global_store_dwordx4 v157, v[106:109], s[76:77] offset:64 nt
	global_load_dwordx4 v[244:247], v157, s[74:75] offset:576 nt
	s_waitcnt vmcnt(10)
	v_pk_fma_f32 v[104:105], v[104:105], v[150:151], v[226:227]
	v_pk_fma_f32 v[102:103], v[102:103], v[148:149], v[224:225]
	global_store_dwordx4 v157, v[102:105], s[76:77] offset:512 nt
	s_add_u32 s74, s74, 0x20000
	s_addc_u32 s75, s75, 0
	global_load_dwordx4 v[224:227], v157, s[74:75] nt
	s_waitcnt vmcnt(10)
	v_pk_fma_f32 v[100:101], v[100:101], v[170:171], v[230:231]
	v_pk_fma_f32 v[98:99], v[98:99], v[168:169], v[228:229]
	global_store_dwordx4 v157, v[98:101], s[76:77] offset:576 nt
	global_load_dwordx4 v[228:231], v157, s[74:75] offset:64 nt
	s_add_u32 s76, s76, 0x20000
	s_addc_u32 s77, s77, 0
	s_waitcnt vmcnt(10)
	v_pk_fma_f32 v[96:97], v[96:97], v[142:143], v[234:235]
	v_pk_fma_f32 v[94:95], v[94:95], v[140:141], v[232:233]
	global_store_dwordx4 v157, v[94:97], s[76:77] nt
	global_load_dwordx4 v[232:235], v157, s[74:75] offset:512 nt
	s_waitcnt vmcnt(10)
	v_pk_fma_f32 v[92:93], v[92:93], v[146:147], v[238:239]
	v_pk_fma_f32 v[90:91], v[90:91], v[144:145], v[236:237]
	global_store_dwordx4 v157, v[90:93], s[76:77] offset:64 nt
	global_load_dwordx4 v[236:239], v157, s[74:75] offset:576 nt
	s_waitcnt vmcnt(10)
	v_pk_fma_f32 v[88:89], v[88:89], v[150:151], v[242:243]
	v_pk_fma_f32 v[86:87], v[86:87], v[148:149], v[240:241]
	global_store_dwordx4 v157, v[86:89], s[76:77] offset:512 nt
	s_add_u32 s74, s74, 0xa0000
	s_addc_u32 s75, s75, 0
	global_load_dwordx4 v[240:243], v157, s[74:75] nt
	s_waitcnt vmcnt(10)
	v_pk_fma_f32 v[84:85], v[84:85], v[170:171], v[246:247]
	v_pk_fma_f32 v[82:83], v[82:83], v[168:169], v[244:245]
	global_store_dwordx4 v157, v[82:85], s[76:77] offset:576 nt
	global_load_dwordx4 v[244:247], v157, s[74:75] offset:64 nt
	s_add_u32 s76, s76, 0x20000
	s_addc_u32 s77, s77, 0
	s_waitcnt vmcnt(10)
	v_pk_fma_f32 v[80:81], v[80:81], v[142:143], v[226:227]
	v_pk_fma_f32 v[78:79], v[78:79], v[140:141], v[224:225]
	global_store_dwordx4 v157, v[78:81], s[76:77] nt
	global_load_dwordx4 v[224:227], v157, s[74:75] offset:512 nt
	s_waitcnt vmcnt(10)
	v_pk_fma_f32 v[76:77], v[76:77], v[146:147], v[230:231]
	v_pk_fma_f32 v[74:75], v[74:75], v[144:145], v[228:229]
	global_store_dwordx4 v157, v[74:77], s[76:77] offset:64 nt
	global_load_dwordx4 v[228:231], v157, s[74:75] offset:576 nt
	s_waitcnt vmcnt(10)
	v_pk_fma_f32 v[72:73], v[72:73], v[150:151], v[234:235]
	v_pk_fma_f32 v[70:71], v[70:71], v[148:149], v[232:233]
	global_store_dwordx4 v157, v[70:73], s[76:77] offset:512 nt
	s_add_u32 s74, s74, 0x20000
	s_addc_u32 s75, s75, 0
	global_load_dwordx4 v[232:235], v157, s[74:75] nt
	s_waitcnt vmcnt(10)
	v_pk_fma_f32 v[68:69], v[68:69], v[170:171], v[238:239]
	v_pk_fma_f32 v[66:67], v[66:67], v[168:169], v[236:237]
	global_store_dwordx4 v157, v[66:69], s[76:77] offset:576 nt
	global_load_dwordx4 v[236:239], v157, s[74:75] offset:64 nt
	s_add_u32 s76, s76, 0xa0000
	s_addc_u32 s77, s77, 0
	s_waitcnt vmcnt(10)
	v_pk_fma_f32 v[64:65], v[64:65], v[142:143], v[242:243]
	v_pk_fma_f32 v[62:63], v[62:63], v[140:141], v[240:241]
	global_store_dwordx4 v157, v[62:65], s[76:77] nt
	global_load_dwordx4 v[240:243], v157, s[74:75] offset:512 nt
	s_waitcnt vmcnt(10)
	v_pk_fma_f32 v[60:61], v[60:61], v[146:147], v[246:247]
	v_pk_fma_f32 v[58:59], v[58:59], v[144:145], v[244:245]
	global_store_dwordx4 v157, v[58:61], s[76:77] offset:64 nt
	global_load_dwordx4 v[244:247], v157, s[74:75] offset:576 nt
	s_waitcnt vmcnt(10)
	v_pk_fma_f32 v[56:57], v[56:57], v[150:151], v[226:227]
	v_pk_fma_f32 v[54:55], v[54:55], v[148:149], v[224:225]
	global_store_dwordx4 v157, v[54:57], s[76:77] offset:512 nt
	s_add_u32 s74, s74, 0x20000
	s_addc_u32 s75, s75, 0
	global_load_dwordx4 v[224:227], v157, s[74:75] nt
	s_waitcnt vmcnt(10)
	v_pk_fma_f32 v[52:53], v[52:53], v[170:171], v[230:231]
	v_pk_fma_f32 v[50:51], v[50:51], v[168:169], v[228:229]
	global_store_dwordx4 v157, v[50:53], s[76:77] offset:576 nt
	global_load_dwordx4 v[228:231], v157, s[74:75] offset:64 nt
	s_add_u32 s76, s76, 0x20000
	s_addc_u32 s77, s77, 0
	s_waitcnt vmcnt(10)
	v_pk_fma_f32 v[48:49], v[48:49], v[142:143], v[234:235]
	v_pk_fma_f32 v[46:47], v[46:47], v[140:141], v[232:233]
	global_store_dwordx4 v157, v[46:49], s[76:77] nt
	global_load_dwordx4 v[232:235], v157, s[74:75] offset:512 nt
	s_waitcnt vmcnt(10)
	v_pk_fma_f32 v[44:45], v[44:45], v[146:147], v[238:239]
	v_pk_fma_f32 v[42:43], v[42:43], v[144:145], v[236:237]
	global_store_dwordx4 v157, v[42:45], s[76:77] offset:64 nt
	global_load_dwordx4 v[236:239], v157, s[74:75] offset:576 nt
	s_waitcnt vmcnt(10)
	v_pk_fma_f32 v[40:41], v[40:41], v[150:151], v[242:243]
	v_pk_fma_f32 v[38:39], v[38:39], v[148:149], v[240:241]
	global_store_dwordx4 v157, v[38:41], s[76:77] offset:512 nt
	s_add_u32 s74, s74, 0x20000
	s_addc_u32 s75, s75, 0
	global_load_dwordx4 v[240:243], v157, s[74:75] nt
	s_waitcnt vmcnt(10)
	v_pk_fma_f32 v[36:37], v[36:37], v[170:171], v[246:247]
	v_pk_fma_f32 v[34:35], v[34:35], v[168:169], v[244:245]
	global_store_dwordx4 v157, v[34:37], s[76:77] offset:576 nt
	global_load_dwordx4 v[244:247], v157, s[74:75] offset:64 nt
	s_add_u32 s76, s76, 0x20000
	s_addc_u32 s77, s77, 0
	s_waitcnt vmcnt(10)
	v_pk_fma_f32 v[32:33], v[32:33], v[142:143], v[226:227]
	v_pk_fma_f32 v[30:31], v[30:31], v[140:141], v[224:225]
	global_store_dwordx4 v157, v[30:33], s[76:77] nt
	global_load_dwordx4 v[224:227], v157, s[74:75] offset:512 nt
	s_waitcnt vmcnt(10)
	v_pk_fma_f32 v[28:29], v[28:29], v[146:147], v[230:231]
	v_pk_fma_f32 v[26:27], v[26:27], v[144:145], v[228:229]
	global_store_dwordx4 v157, v[26:29], s[76:77] offset:64 nt
	global_load_dwordx4 v[228:231], v157, s[74:75] offset:576 nt
	s_waitcnt vmcnt(10)
	v_pk_fma_f32 v[24:25], v[24:25], v[150:151], v[234:235]
	v_pk_fma_f32 v[22:23], v[22:23], v[148:149], v[232:233]
	global_store_dwordx4 v157, v[22:25], s[76:77] offset:512 nt
	s_waitcnt vmcnt(9)
	v_pk_fma_f32 v[20:21], v[20:21], v[170:171], v[238:239]
	v_pk_fma_f32 v[18:19], v[18:19], v[168:169], v[236:237]
	global_store_dwordx4 v157, v[18:21], s[76:77] offset:576 nt
	s_add_u32 s76, s76, 0x20000
	s_addc_u32 s77, s77, 0
	s_waitcnt vmcnt(8)
	v_pk_fma_f32 v[16:17], v[16:17], v[142:143], v[242:243]
	v_pk_fma_f32 v[14:15], v[14:15], v[140:141], v[240:241]
	global_store_dwordx4 v157, v[14:17], s[76:77] nt
	s_waitcnt vmcnt(7)
	v_pk_fma_f32 v[12:13], v[12:13], v[146:147], v[246:247]
	v_pk_fma_f32 v[10:11], v[10:11], v[144:145], v[244:245]
	global_store_dwordx4 v157, v[10:13], s[76:77] offset:64 nt
	s_waitcnt vmcnt(6)
	v_pk_fma_f32 v[8:9], v[8:9], v[150:151], v[226:227]
	v_pk_fma_f32 v[6:7], v[6:7], v[148:149], v[224:225]
	global_store_dwordx4 v157, v[6:9], s[76:77] offset:512 nt
	s_waitcnt vmcnt(5)
	v_pk_fma_f32 v[4:5], v[4:5], v[170:171], v[230:231]
	v_pk_fma_f32 v[2:3], v[2:3], v[168:169], v[228:229]
	global_store_dwordx4 v157, v[2:5], s[76:77] offset:576 nt
	s_branch .LBB0_24

.LBB0_234:
	s_add_u32 s39, s46, 0xfff80080
	s_addc_u32 s48, s47, -1
	s_add_i32 s62, 0, 0x10000
	v_add_u32_e32 v156, s62, v141
	ds_read_b128 v[144:147], v156
	ds_read_b128 v[148:151], v156 offset:1024
	ds_read_b128 v[152:155], v156 offset:2048
	ds_read_b128 v[168:171], v156 offset:3072
	s_cmp_eq_u32 s13, 28
	s_cselect_b32 s51, s43, s48
	s_cselect_b32 s50, s42, s39
	s_cselect_b32 s49, s45, s12
	s_cselect_b32 s48, s44, s1
	s_add_i32 m0, s53, 0xc000
	ds_read_b128 v[172:175], v143
	ds_read_b128 v[176:179], v143 offset:1024
	ds_read_b128 v[180:183], v143 offset:2048
	ds_read_b128 v[184:187], v143 offset:3072
	ds_read_b128 v[188:191], v143 offset:4096
	ds_read_b128 v[192:195], v143 offset:5120
	ds_read_b128 v[196:199], v143 offset:6144
	ds_read_b128 v[224:227], v143 offset:7168
	global_load_lds_dwordx4 v136, s[46:47]
	s_add_i32 m0, s53, 0xe000
	s_nop 0
	global_load_lds_dwordx4 v138, s[46:47]
	s_waitcnt lgkmcnt(8)
	s_barrier
	s_waitcnt lgkmcnt(0)
	s_waitcnt lgkmcnt(0)
	v_mfma_f32_16x16x32_bf16 v[126:129], v[144:147], v[172:175], v[126:129]
	v_mfma_f32_16x16x32_bf16 v[122:125], v[152:155], v[172:175], v[122:125]
	v_mfma_f32_16x16x32_bf16 v[118:121], v[144:147], v[180:183], v[118:121]
	v_mfma_f32_16x16x32_bf16 v[114:117], v[152:155], v[180:183], v[114:117]
	v_mfma_f32_16x16x32_bf16 v[102:105], v[144:147], v[188:191], v[102:105]
	v_mfma_f32_16x16x32_bf16 v[98:101], v[152:155], v[188:191], v[98:101]
	v_mfma_f32_16x16x32_bf16 v[86:89], v[144:147], v[196:199], v[86:89]
	v_mfma_f32_16x16x32_bf16 v[82:85], v[152:155], v[196:199], v[82:85]
	v_mfma_f32_16x16x32_bf16 v[126:129], v[148:151], v[176:179], v[126:129]
	v_mfma_f32_16x16x32_bf16 v[122:125], v[168:171], v[176:179], v[122:125]
	v_mfma_f32_16x16x32_bf16 v[118:121], v[148:151], v[184:187], v[118:121]
	v_mfma_f32_16x16x32_bf16 v[114:117], v[168:171], v[184:187], v[114:117]
	v_mfma_f32_16x16x32_bf16 v[102:105], v[148:151], v[192:195], v[102:105]
	v_mfma_f32_16x16x32_bf16 v[98:101], v[168:171], v[192:195], v[98:101]
	v_mfma_f32_16x16x32_bf16 v[86:89], v[148:151], v[224:227], v[86:89]
	v_mfma_f32_16x16x32_bf16 v[82:85], v[168:171], v[224:227], v[82:85]
	s_barrier
	s_add_i32 s39, 0, 0x14000
	v_add_u32_e32 v156, s39, v141
	s_add_i32 s62, s62, s52
	ds_read_b128 v[228:231], v156
	ds_read_b128 v[232:235], v156 offset:1024
	ds_read_b128 v[236:239], v156 offset:2048
	ds_read_b128 v[240:243], v156 offset:3072
	s_add_u32 s76, s48, s94
	s_addc_u32 s77, s49, s95
	s_mov_b32 m0, s62
	s_nop 0
	global_load_lds_dwordx4 v0, s[48:49]
	s_add_i32 m0, s62, 0x2000
	s_nop 0
	global_load_lds_dwordx4 v130, s[48:49]
	s_barrier
	s_waitcnt lgkmcnt(0)
	s_waitcnt lgkmcnt(0)
	v_mfma_f32_16x16x32_bf16 v[110:113], v[228:231], v[172:175], v[110:113]
	v_mfma_f32_16x16x32_bf16 v[106:109], v[236:239], v[172:175], v[106:109]
	v_mfma_f32_16x16x32_bf16 v[94:97], v[228:231], v[180:183], v[94:97]
	v_mfma_f32_16x16x32_bf16 v[90:93], v[236:239], v[180:183], v[90:93]
	v_mfma_f32_16x16x32_bf16 v[78:81], v[228:231], v[188:191], v[78:81]
	v_mfma_f32_16x16x32_bf16 v[74:77], v[236:239], v[188:191], v[74:77]
	v_mfma_f32_16x16x32_bf16 v[70:73], v[228:231], v[196:199], v[70:73]
	v_mfma_f32_16x16x32_bf16 v[66:69], v[236:239], v[196:199], v[66:69]
	v_mfma_f32_16x16x32_bf16 v[110:113], v[232:235], v[176:179], v[110:113]
	v_mfma_f32_16x16x32_bf16 v[106:109], v[240:243], v[176:179], v[106:109]
	v_mfma_f32_16x16x32_bf16 v[94:97], v[232:235], v[184:187], v[94:97]
	v_mfma_f32_16x16x32_bf16 v[90:93], v[240:243], v[184:187], v[90:93]
	v_mfma_f32_16x16x32_bf16 v[78:81], v[232:235], v[192:195], v[78:81]
	v_mfma_f32_16x16x32_bf16 v[74:77], v[240:243], v[192:195], v[74:77]
	v_mfma_f32_16x16x32_bf16 v[70:73], v[232:235], v[224:227], v[70:73]
	v_mfma_f32_16x16x32_bf16 v[66:69], v[240:243], v[224:227], v[66:69]
	s_mov_b32 m0, s53
	s_add_u32 s78, s50, s94
	s_addc_u32 s79, s51, s95
	s_barrier
	ds_read_b128 v[172:175], v143 offset:16384
	ds_read_b128 v[176:179], v143 offset:17408
	ds_read_b128 v[180:183], v143 offset:18432
	ds_read_b128 v[184:187], v143 offset:19456
	ds_read_b128 v[188:191], v143 offset:20480
	ds_read_b128 v[192:195], v143 offset:21504
	ds_read_b128 v[196:199], v143 offset:22528
	ds_read_b128 v[224:227], v143 offset:23552
	global_load_lds_dwordx4 v134, s[50:51]
	s_mov_b32 m0, s54
	s_nop 0
	global_load_lds_dwordx4 v132, s[50:51]
	s_barrier
	s_waitcnt lgkmcnt(0)
	s_waitcnt lgkmcnt(0)
	v_mfma_f32_16x16x32_bf16 v[62:65], v[144:147], v[172:175], v[62:65]
	v_mfma_f32_16x16x32_bf16 v[58:61], v[152:155], v[172:175], v[58:61]
	v_mfma_f32_16x16x32_bf16 v[54:57], v[144:147], v[180:183], v[54:57]
	v_mfma_f32_16x16x32_bf16 v[50:53], v[152:155], v[180:183], v[50:53]
	v_mfma_f32_16x16x32_bf16 v[38:41], v[144:147], v[188:191], v[38:41]
	v_mfma_f32_16x16x32_bf16 v[34:37], v[152:155], v[188:191], v[34:37]
	v_mfma_f32_16x16x32_bf16 v[22:25], v[144:147], v[196:199], v[22:25]
	v_mfma_f32_16x16x32_bf16 v[18:21], v[152:155], v[196:199], v[18:21]
	v_mfma_f32_16x16x32_bf16 v[62:65], v[148:151], v[176:179], v[62:65]
	v_mfma_f32_16x16x32_bf16 v[58:61], v[168:171], v[176:179], v[58:61]
	v_mfma_f32_16x16x32_bf16 v[54:57], v[148:151], v[184:187], v[54:57]
	v_mfma_f32_16x16x32_bf16 v[50:53], v[168:171], v[184:187], v[50:53]
	v_mfma_f32_16x16x32_bf16 v[38:41], v[148:151], v[192:195], v[38:41]
	v_mfma_f32_16x16x32_bf16 v[34:37], v[168:171], v[192:195], v[34:37]
	v_mfma_f32_16x16x32_bf16 v[22:25], v[148:151], v[224:227], v[22:25]
	v_mfma_f32_16x16x32_bf16 v[18:21], v[168:171], v[224:227], v[18:21]
	s_barrier
	s_add_u32 s62, s48, 0x80000
	s_addc_u32 s63, s49, 0
	s_add_i32 s39, s39, s52
	s_mov_b32 m0, s39
	s_nop 0
	global_load_lds_dwordx4 v0, s[62:63]
	s_add_i32 m0, s39, 0x2000
	s_nop 0
	global_load_lds_dwordx4 v130, s[62:63]
	s_waitcnt vmcnt(6)
	s_barrier
	v_mfma_f32_16x16x32_bf16 v[46:49], v[228:231], v[172:175], v[46:49]
	v_mfma_f32_16x16x32_bf16 v[42:45], v[236:239], v[172:175], v[42:45]
	v_mfma_f32_16x16x32_bf16 v[30:33], v[228:231], v[180:183], v[30:33]
	v_mfma_f32_16x16x32_bf16 v[26:29], v[236:239], v[180:183], v[26:29]
	v_mfma_f32_16x16x32_bf16 v[14:17], v[228:231], v[188:191], v[14:17]
	v_mfma_f32_16x16x32_bf16 v[10:13], v[236:239], v[188:191], v[10:13]
	v_mfma_f32_16x16x32_bf16 v[6:9], v[228:231], v[196:199], v[6:9]
	v_mfma_f32_16x16x32_bf16 v[2:5], v[236:239], v[196:199], v[2:5]
	v_mfma_f32_16x16x32_bf16 v[46:49], v[232:235], v[176:179], v[46:49]
	v_mfma_f32_16x16x32_bf16 v[42:45], v[240:243], v[176:179], v[42:45]
	v_mfma_f32_16x16x32_bf16 v[30:33], v[232:235], v[184:187], v[30:33]
	v_mfma_f32_16x16x32_bf16 v[26:29], v[240:243], v[184:187], v[26:29]
	v_mfma_f32_16x16x32_bf16 v[14:17], v[232:235], v[192:195], v[14:17]
	v_mfma_f32_16x16x32_bf16 v[10:13], v[240:243], v[192:195], v[10:13]
	v_mfma_f32_16x16x32_bf16 v[6:9], v[232:235], v[224:227], v[6:9]
	v_mfma_f32_16x16x32_bf16 v[2:5], v[240:243], v[224:227], v[2:5]
	s_add_i32 s39, 0, 0x18000
	v_add_u32_e32 v161, s39, v141
	s_barrier
	ds_read_b128 v[144:147], v161
	ds_read_b128 v[148:151], v161 offset:1024
	ds_read_b128 v[152:155], v161 offset:2048
	ds_read_b128 v[168:171], v161 offset:3072
	s_add_u32 s50, s50, 0x80000
	s_addc_u32 s51, s51, 0
	s_mov_b32 m0, s55
	ds_read_b128 v[172:175], v143 offset:32768
	ds_read_b128 v[176:179], v143 offset:33792
	ds_read_b128 v[180:183], v143 offset:34816
	ds_read_b128 v[184:187], v143 offset:35840
	ds_read_b128 v[188:191], v143 offset:36864
	ds_read_b128 v[192:195], v143 offset:37888
	ds_read_b128 v[196:199], v143 offset:38912
	ds_read_b128 v[224:227], v143 offset:39936
	global_load_lds_dwordx4 v134, s[50:51]
	s_mov_b32 m0, s56
	s_nop 0
	global_load_lds_dwordx4 v132, s[50:51]
	s_waitcnt lgkmcnt(8)
	s_barrier
	s_waitcnt lgkmcnt(0)
	s_waitcnt lgkmcnt(0)
	v_mfma_f32_16x16x32_bf16 v[126:129], v[144:147], v[172:175], v[126:129]
	v_mfma_f32_16x16x32_bf16 v[122:125], v[152:155], v[172:175], v[122:125]
	v_mfma_f32_16x16x32_bf16 v[118:121], v[144:147], v[180:183], v[118:121]
	v_mfma_f32_16x16x32_bf16 v[114:117], v[152:155], v[180:183], v[114:117]
	v_mfma_f32_16x16x32_bf16 v[102:105], v[144:147], v[188:191], v[102:105]
	v_mfma_f32_16x16x32_bf16 v[98:101], v[152:155], v[188:191], v[98:101]
	v_mfma_f32_16x16x32_bf16 v[86:89], v[144:147], v[196:199], v[86:89]
	v_mfma_f32_16x16x32_bf16 v[82:85], v[152:155], v[196:199], v[82:85]
	v_mfma_f32_16x16x32_bf16 v[126:129], v[148:151], v[176:179], v[126:129]
	v_mfma_f32_16x16x32_bf16 v[122:125], v[168:171], v[176:179], v[122:125]
	v_mfma_f32_16x16x32_bf16 v[118:121], v[148:151], v[184:187], v[118:121]
	v_mfma_f32_16x16x32_bf16 v[114:117], v[168:171], v[184:187], v[114:117]
	v_mfma_f32_16x16x32_bf16 v[102:105], v[148:151], v[192:195], v[102:105]
	v_mfma_f32_16x16x32_bf16 v[98:101], v[168:171], v[192:195], v[98:101]
	v_mfma_f32_16x16x32_bf16 v[86:89], v[148:151], v[224:227], v[86:89]
	v_mfma_f32_16x16x32_bf16 v[82:85], v[168:171], v[224:227], v[82:85]
	s_barrier
	s_add_i32 s50, 0, 0x1c000
	s_add_i32 s39, s39, s52
	v_add_u32_e32 v161, s50, v141
	s_mov_b32 m0, s39
	ds_read_b128 v[228:231], v161
	ds_read_b128 v[232:235], v161 offset:1024
	ds_read_b128 v[236:239], v161 offset:2048
	ds_read_b128 v[240:243], v161 offset:3072
	global_load_lds_dwordx4 v0, s[76:77]
	s_add_i32 m0, s39, 0x2000
	s_nop 0
	global_load_lds_dwordx4 v130, s[76:77]
	s_barrier
	s_waitcnt lgkmcnt(0)
	s_waitcnt lgkmcnt(0)
	v_mfma_f32_16x16x32_bf16 v[110:113], v[228:231], v[172:175], v[110:113]
	v_mfma_f32_16x16x32_bf16 v[106:109], v[236:239], v[172:175], v[106:109]
	v_mfma_f32_16x16x32_bf16 v[94:97], v[228:231], v[180:183], v[94:97]
	v_mfma_f32_16x16x32_bf16 v[90:93], v[236:239], v[180:183], v[90:93]
	v_mfma_f32_16x16x32_bf16 v[78:81], v[228:231], v[188:191], v[78:81]
	v_mfma_f32_16x16x32_bf16 v[74:77], v[236:239], v[188:191], v[74:77]
	v_mfma_f32_16x16x32_bf16 v[70:73], v[228:231], v[196:199], v[70:73]
	v_mfma_f32_16x16x32_bf16 v[66:69], v[236:239], v[196:199], v[66:69]
	v_mfma_f32_16x16x32_bf16 v[110:113], v[232:235], v[176:179], v[110:113]
	v_mfma_f32_16x16x32_bf16 v[106:109], v[240:243], v[176:179], v[106:109]
	v_mfma_f32_16x16x32_bf16 v[94:97], v[232:235], v[184:187], v[94:97]
	v_mfma_f32_16x16x32_bf16 v[90:93], v[240:243], v[184:187], v[90:93]
	v_mfma_f32_16x16x32_bf16 v[78:81], v[232:235], v[192:195], v[78:81]
	v_mfma_f32_16x16x32_bf16 v[74:77], v[240:243], v[192:195], v[74:77]
	v_mfma_f32_16x16x32_bf16 v[70:73], v[232:235], v[224:227], v[70:73]
	v_mfma_f32_16x16x32_bf16 v[66:69], v[240:243], v[224:227], v[66:69]
	s_mov_b32 m0, s57
	s_barrier
	ds_read_b128 v[172:175], v143 offset:49152
	ds_read_b128 v[176:179], v143 offset:50176
	ds_read_b128 v[180:183], v143 offset:51200
	ds_read_b128 v[184:187], v143 offset:52224
	ds_read_b128 v[188:191], v143 offset:53248
	ds_read_b128 v[192:195], v143 offset:54272
	ds_read_b128 v[196:199], v143 offset:55296
	ds_read_b128 v[224:227], v143 offset:56320
	global_load_lds_dwordx4 v134, s[78:79]
	s_mov_b32 m0, s58
	s_nop 0
	global_load_lds_dwordx4 v132, s[78:79]
	s_barrier
	s_waitcnt lgkmcnt(0)
	s_waitcnt lgkmcnt(0)
	v_mfma_f32_16x16x32_bf16 v[62:65], v[144:147], v[172:175], v[62:65]
	v_mfma_f32_16x16x32_bf16 v[58:61], v[152:155], v[172:175], v[58:61]
	v_mfma_f32_16x16x32_bf16 v[54:57], v[144:147], v[180:183], v[54:57]
	v_mfma_f32_16x16x32_bf16 v[50:53], v[152:155], v[180:183], v[50:53]
	v_mfma_f32_16x16x32_bf16 v[38:41], v[144:147], v[188:191], v[38:41]
	v_mfma_f32_16x16x32_bf16 v[34:37], v[152:155], v[188:191], v[34:37]
	v_mfma_f32_16x16x32_bf16 v[22:25], v[144:147], v[196:199], v[22:25]
	v_mfma_f32_16x16x32_bf16 v[18:21], v[152:155], v[196:199], v[18:21]
	v_mfma_f32_16x16x32_bf16 v[62:65], v[148:151], v[176:179], v[62:65]
	v_mfma_f32_16x16x32_bf16 v[58:61], v[168:171], v[176:179], v[58:61]
	v_mfma_f32_16x16x32_bf16 v[54:57], v[148:151], v[184:187], v[54:57]
	v_mfma_f32_16x16x32_bf16 v[50:53], v[168:171], v[184:187], v[50:53]
	v_mfma_f32_16x16x32_bf16 v[38:41], v[148:151], v[192:195], v[38:41]
	v_mfma_f32_16x16x32_bf16 v[34:37], v[168:171], v[192:195], v[34:37]
	v_mfma_f32_16x16x32_bf16 v[22:25], v[148:151], v[224:227], v[22:25]
	v_mfma_f32_16x16x32_bf16 v[18:21], v[168:171], v[224:227], v[18:21]
	s_barrier
	s_add_u32 s48, s48, 0x80080
	s_addc_u32 s49, s49, 0
	s_add_i32 s39, s50, s52
	s_mov_b32 m0, s39
	s_nop 0
	global_load_lds_dwordx4 v0, s[48:49]
	s_add_i32 m0, s39, 0x2000
	s_nop 0
	global_load_lds_dwordx4 v130, s[48:49]
	s_waitcnt vmcnt(6)
	s_barrier
	v_mfma_f32_16x16x32_bf16 v[46:49], v[228:231], v[172:175], v[46:49]
	v_mfma_f32_16x16x32_bf16 v[42:45], v[236:239], v[172:175], v[42:45]
	v_mfma_f32_16x16x32_bf16 v[30:33], v[228:231], v[180:183], v[30:33]
	v_mfma_f32_16x16x32_bf16 v[26:29], v[236:239], v[180:183], v[26:29]
	v_mfma_f32_16x16x32_bf16 v[14:17], v[228:231], v[188:191], v[14:17]
	v_mfma_f32_16x16x32_bf16 v[10:13], v[236:239], v[188:191], v[10:13]
	v_mfma_f32_16x16x32_bf16 v[6:9], v[228:231], v[196:199], v[6:9]
	v_mfma_f32_16x16x32_bf16 v[2:5], v[236:239], v[196:199], v[2:5]
	v_mfma_f32_16x16x32_bf16 v[46:49], v[232:235], v[176:179], v[46:49]
	v_mfma_f32_16x16x32_bf16 v[42:45], v[240:243], v[176:179], v[42:45]
	v_mfma_f32_16x16x32_bf16 v[30:33], v[232:235], v[184:187], v[30:33]
	v_mfma_f32_16x16x32_bf16 v[26:29], v[240:243], v[184:187], v[26:29]
	v_mfma_f32_16x16x32_bf16 v[14:17], v[232:235], v[192:195], v[14:17]
	v_mfma_f32_16x16x32_bf16 v[10:13], v[240:243], v[192:195], v[10:13]
	v_mfma_f32_16x16x32_bf16 v[6:9], v[232:235], v[224:227], v[6:9]
	v_mfma_f32_16x16x32_bf16 v[2:5], v[240:243], v[224:227], v[2:5]
	s_add_i32 s13, s13, 2
	s_add_u32 s46, s46, 0x100
	s_addc_u32 s47, s47, 0
	s_add_u32 s1, s1, 0x100
	s_addc_u32 s12, s12, 0
	s_cmp_gt_u32 s13, 29
	s_barrier
	s_cbranch_scc0 .LBB0_234
	v_readlane_b32 s6, v255, 23
	v_lshl_add_u32 v150, s61, 8, v140
	v_lshl_or_b32 v144, s60, 8, v142
	v_readlane_b32 s7, v255, 24
	v_ashrrev_i32_e32 v145, 31, v144
	s_movk_i32 s1, 0x5800
	v_mov_b64_e32 v[146:147], s[6:7]
	v_cvt_pk_bf16_f32 v70, v70, v71
	v_cvt_pk_bf16_f32 v71, v72, v73
	v_cvt_pk_bf16_f32 v72, v66, v67
	v_add_u32_e32 v66, 0x80, v150
	v_mad_i64_i32 v[148:149], s[12:13], v150, s1, v[146:147]
	v_lshlrev_b64 v[144:145], 1, v[144:145]
	v_cvt_pk_bf16_f32 v110, v110, v111
	v_cvt_pk_bf16_f32 v111, v112, v113
	v_cvt_pk_bf16_f32 v112, v106, v107
	v_or_b32_e32 v106, 16, v150
	v_mad_i64_i32 v[66:67], s[12:13], v66, s1, v[146:147]
	v_cvt_pk_bf16_f32 v46, v46, v47
	v_cvt_pk_bf16_f32 v47, v48, v49
	v_cvt_pk_bf16_f32 v48, v42, v43
	v_add_u32_e32 v42, 0x90, v150
	v_lshl_add_u64 v[148:149], v[148:149], 0, v[144:145]
	v_cvt_pk_bf16_f32 v113, v108, v109
	v_mad_i64_i32 v[106:107], s[12:13], v106, s1, v[146:147]
	v_cvt_pk_bf16_f32 v94, v94, v95
	v_cvt_pk_bf16_f32 v95, v96, v97
	v_cvt_pk_bf16_f32 v96, v90, v91
	v_or_b32_e32 v90, 32, v150
	v_lshl_add_u64 v[66:67], v[66:67], 0, v[144:145]
	v_cvt_pk_bf16_f32 v49, v44, v45
	v_mad_i64_i32 v[42:43], s[12:13], v42, s1, v[146:147]
	v_cvt_pk_bf16_f32 v30, v30, v31
	v_cvt_pk_bf16_f32 v31, v32, v33
	v_cvt_pk_bf16_f32 v32, v26, v27
	v_add_u32_e32 v26, 0xa0, v150
	global_store_dwordx4 v[148:149], v[110:113], off offset:256
	v_cvt_pk_bf16_f32 v97, v92, v93
	v_mad_i64_i32 v[90:91], s[12:13], v90, s1, v[146:147]
	v_lshl_add_u64 v[110:111], v[106:107], 0, v[144:145]
	v_cvt_pk_bf16_f32 v78, v78, v79
	v_cvt_pk_bf16_f32 v79, v80, v81
	v_cvt_pk_bf16_f32 v80, v74, v75
	v_or_b32_e32 v74, 48, v150
	global_store_dwordx4 v[66:67], v[46:49], off offset:256
	v_cvt_pk_bf16_f32 v33, v28, v29
	v_mad_i64_i32 v[26:27], s[12:13], v26, s1, v[146:147]
	v_lshl_add_u64 v[46:47], v[42:43], 0, v[144:145]
	v_cvt_pk_bf16_f32 v14, v14, v15
	v_cvt_pk_bf16_f32 v15, v16, v17
	v_cvt_pk_bf16_f32 v16, v10, v11
	v_add_u32_e32 v10, 0xb0, v150
	global_store_dwordx4 v[110:111], v[94:97], off offset:256
	v_cvt_pk_bf16_f32 v81, v76, v77
	v_mad_i64_i32 v[74:75], s[12:13], v74, s1, v[146:147]
	v_lshl_add_u64 v[94:95], v[90:91], 0, v[144:145]
	global_store_dwordx4 v[46:47], v[30:33], off offset:256
	v_cvt_pk_bf16_f32 v17, v12, v13
	v_mad_i64_i32 v[10:11], s[12:13], v10, s1, v[146:147]
	v_lshl_add_u64 v[30:31], v[26:27], 0, v[144:145]
	v_cvt_pk_bf16_f32 v126, v126, v127
	v_cvt_pk_bf16_f32 v127, v128, v129
	v_cvt_pk_bf16_f32 v128, v122, v123
	v_cvt_pk_bf16_f32 v129, v124, v125
	v_cvt_pk_bf16_f32 v106, v118, v119
	v_cvt_pk_bf16_f32 v107, v120, v121
	v_cvt_pk_bf16_f32 v108, v114, v115
	v_cvt_pk_bf16_f32 v109, v116, v117
	v_cvt_pk_bf16_f32 v90, v102, v103
	v_cvt_pk_bf16_f32 v91, v104, v105
	v_cvt_pk_bf16_f32 v92, v98, v99
	v_cvt_pk_bf16_f32 v93, v100, v101
	global_store_dwordx4 v[94:95], v[78:81], off offset:256
	v_cvt_pk_bf16_f32 v76, v82, v83
	v_cvt_pk_bf16_f32 v77, v84, v85
	v_lshl_add_u64 v[78:79], v[74:75], 0, v[144:145]
	v_cvt_pk_bf16_f32 v74, v86, v87
	v_cvt_pk_bf16_f32 v75, v88, v89
	v_cvt_pk_bf16_f32 v73, v68, v69
	v_cvt_pk_bf16_f32 v62, v62, v63
	v_cvt_pk_bf16_f32 v63, v64, v65
	v_cvt_pk_bf16_f32 v64, v58, v59
	v_cvt_pk_bf16_f32 v65, v60, v61
	v_cvt_pk_bf16_f32 v42, v54, v55
	v_cvt_pk_bf16_f32 v43, v56, v57
	v_cvt_pk_bf16_f32 v44, v50, v51
	v_cvt_pk_bf16_f32 v45, v52, v53
	v_cvt_pk_bf16_f32 v26, v38, v39
	v_cvt_pk_bf16_f32 v27, v40, v41
	v_cvt_pk_bf16_f32 v28, v34, v35
	v_cvt_pk_bf16_f32 v29, v36, v37
	global_store_dwordx4 v[30:31], v[14:17], off offset:256
	v_cvt_pk_bf16_f32 v12, v18, v19
	v_cvt_pk_bf16_f32 v13, v20, v21
	v_lshl_add_u64 v[14:15], v[10:11], 0, v[144:145]
	v_cvt_pk_bf16_f32 v10, v22, v23
	v_cvt_pk_bf16_f32 v11, v24, v25
	v_cvt_pk_bf16_f32 v6, v6, v7
	v_cvt_pk_bf16_f32 v7, v8, v9
	v_cvt_pk_bf16_f32 v8, v2, v3
	v_cvt_pk_bf16_f32 v9, v4, v5
	s_and_b64 vcc, exec, s[40:41]
	s_mov_b32 s60, s0
	s_mov_b32 s61, s38
	s_mov_b64 s[48:49], s[44:45]
	s_mov_b64 s[46:47], s[42:43]
	global_store_dwordx4 v[148:149], v[126:129], off
	global_store_dwordx4 v[110:111], v[106:109], off
	global_store_dwordx4 v[94:95], v[90:93], off
	global_store_dwordx4 v[78:79], v[74:77], off
	global_store_dwordx4 v[78:79], v[70:73], off offset:256
	global_store_dwordx4 v[66:67], v[62:65], off
	global_store_dwordx4 v[46:47], v[42:45], off
	global_store_dwordx4 v[30:31], v[26:29], off
	global_store_dwordx4 v[14:15], v[10:13], off
	global_store_dwordx4 v[14:15], v[6:9], off offset:256
	s_cbranch_vccz .LBB0_227
	s_waitcnt vmcnt(0)
	v_readlane_b32 s60, v255, 21
	s_cmpk_gt_u32 s36, 0xff
	s_mov_b32 s18, s60
	v_readlane_b32 s61, v255, 22
	s_cbranch_scc1 .LBB0_238
	s_barrier

.LBB0_282:
	s_add_i32 s67, s50, 2
	s_add_u32 s51, s0, 0xfff80080
	s_addc_u32 s52, s1, -1
	s_add_i32 s68, 0, 0x10000
	v_add_u32_e32 v148, s68, v153
	ds_read_b128 v[136:139], v148
	ds_read_b128 v[140:143], v148 offset:1024
	ds_read_b128 v[144:147], v148 offset:2048
	ds_read_b128 v[148:151], v148 offset:3072
	s_cmp_eq_u32 s12, s50
	s_cselect_b32 s50, s48, s13
	s_cselect_b32 s53, s47, s52
	s_cselect_b32 s52, s46, s51
	s_cselect_b32 s51, s49, s66
	s_add_i32 m0, s55, 0xc000
	ds_read_b128 v[168:171], v155
	ds_read_b128 v[172:175], v155 offset:1024
	ds_read_b128 v[176:179], v155 offset:2048
	ds_read_b128 v[180:183], v155 offset:3072
	ds_read_b128 v[184:187], v155 offset:4096
	ds_read_b128 v[188:191], v155 offset:5120
	ds_read_b128 v[192:195], v155 offset:6144
	ds_read_b128 v[196:199], v155 offset:7168
	global_load_lds_dwordx4 v132, s[0:1]
	s_add_i32 m0, s55, 0xe000
	s_nop 0
	global_load_lds_dwordx4 v134, s[0:1]
	s_waitcnt lgkmcnt(8)
	s_barrier
	s_waitcnt lgkmcnt(0)
	s_waitcnt lgkmcnt(0)
	v_mfma_f32_16x16x32_bf16 v[126:129], v[136:139], v[168:171], v[126:129]
	v_mfma_f32_16x16x32_bf16 v[122:125], v[144:147], v[168:171], v[122:125]
	v_mfma_f32_16x16x32_bf16 v[110:113], v[136:139], v[176:179], v[110:113]
	v_mfma_f32_16x16x32_bf16 v[106:109], v[144:147], v[176:179], v[106:109]
	v_mfma_f32_16x16x32_bf16 v[94:97], v[136:139], v[184:187], v[94:97]
	v_mfma_f32_16x16x32_bf16 v[90:93], v[144:147], v[184:187], v[90:93]
	v_mfma_f32_16x16x32_bf16 v[78:81], v[136:139], v[192:195], v[78:81]
	v_mfma_f32_16x16x32_bf16 v[74:77], v[144:147], v[192:195], v[74:77]
	v_mfma_f32_16x16x32_bf16 v[126:129], v[140:143], v[172:175], v[126:129]
	v_mfma_f32_16x16x32_bf16 v[122:125], v[148:151], v[172:175], v[122:125]
	v_mfma_f32_16x16x32_bf16 v[110:113], v[140:143], v[180:183], v[110:113]
	v_mfma_f32_16x16x32_bf16 v[106:109], v[148:151], v[180:183], v[106:109]
	v_mfma_f32_16x16x32_bf16 v[94:97], v[140:143], v[188:191], v[94:97]
	v_mfma_f32_16x16x32_bf16 v[90:93], v[148:151], v[188:191], v[90:93]
	v_mfma_f32_16x16x32_bf16 v[78:81], v[140:143], v[196:199], v[78:81]
	v_mfma_f32_16x16x32_bf16 v[74:77], v[148:151], v[196:199], v[74:77]
	s_barrier
	s_add_i32 s70, 0, 0x14000
	v_add_u32_e32 v156, s70, v153
	s_add_i32 s68, s68, s54
	ds_read_b128 v[224:227], v156
	ds_read_b128 v[228:231], v156 offset:1024
	ds_read_b128 v[232:235], v156 offset:2048
	ds_read_b128 v[236:239], v156 offset:3072
	s_add_u32 s76, s50, s94
	s_addc_u32 s77, s51, s95
	s_mov_b32 m0, s68
	s_nop 0
	global_load_lds_dwordx4 v0, s[50:51]
	s_add_i32 m0, s68, 0x2000
	s_nop 0
	global_load_lds_dwordx4 v130, s[50:51]
	s_barrier
	s_waitcnt lgkmcnt(0)
	s_waitcnt lgkmcnt(0)
	v_mfma_f32_16x16x32_bf16 v[118:121], v[224:227], v[168:171], v[118:121]
	v_mfma_f32_16x16x32_bf16 v[114:117], v[232:235], v[168:171], v[114:117]
	v_mfma_f32_16x16x32_bf16 v[102:105], v[224:227], v[176:179], v[102:105]
	v_mfma_f32_16x16x32_bf16 v[98:101], v[232:235], v[176:179], v[98:101]
	v_mfma_f32_16x16x32_bf16 v[86:89], v[224:227], v[184:187], v[86:89]
	v_mfma_f32_16x16x32_bf16 v[82:85], v[232:235], v[184:187], v[82:85]
	v_mfma_f32_16x16x32_bf16 v[70:73], v[224:227], v[192:195], v[70:73]
	v_mfma_f32_16x16x32_bf16 v[66:69], v[232:235], v[192:195], v[66:69]
	v_mfma_f32_16x16x32_bf16 v[118:121], v[228:231], v[172:175], v[118:121]
	v_mfma_f32_16x16x32_bf16 v[114:117], v[236:239], v[172:175], v[114:117]
	v_mfma_f32_16x16x32_bf16 v[102:105], v[228:231], v[180:183], v[102:105]
	v_mfma_f32_16x16x32_bf16 v[98:101], v[236:239], v[180:183], v[98:101]
	v_mfma_f32_16x16x32_bf16 v[86:89], v[228:231], v[188:191], v[86:89]
	v_mfma_f32_16x16x32_bf16 v[82:85], v[236:239], v[188:191], v[82:85]
	v_mfma_f32_16x16x32_bf16 v[70:73], v[228:231], v[196:199], v[70:73]
	v_mfma_f32_16x16x32_bf16 v[66:69], v[236:239], v[196:199], v[66:69]
	s_mov_b32 m0, s55
	s_add_u32 s78, s52, s94
	s_addc_u32 s79, s53, s95
	s_barrier
	ds_read_b128 v[168:171], v155 offset:16384
	ds_read_b128 v[172:175], v155 offset:17408
	ds_read_b128 v[176:179], v155 offset:18432
	ds_read_b128 v[180:183], v155 offset:19456
	ds_read_b128 v[184:187], v155 offset:20480
	ds_read_b128 v[188:191], v155 offset:21504
	ds_read_b128 v[192:195], v155 offset:22528
	ds_read_b128 v[196:199], v155 offset:23552
	global_load_lds_dwordx4 v0, s[52:53]
	s_mov_b32 m0, s56
	s_nop 0
	global_load_lds_dwordx4 v130, s[52:53]
	s_barrier
	s_waitcnt lgkmcnt(0)
	s_waitcnt lgkmcnt(0)
	v_mfma_f32_16x16x32_bf16 v[62:65], v[136:139], v[168:171], v[62:65]
	v_mfma_f32_16x16x32_bf16 v[58:61], v[144:147], v[168:171], v[58:61]
	v_mfma_f32_16x16x32_bf16 v[46:49], v[136:139], v[176:179], v[46:49]
	v_mfma_f32_16x16x32_bf16 v[42:45], v[144:147], v[176:179], v[42:45]
	v_mfma_f32_16x16x32_bf16 v[30:33], v[136:139], v[184:187], v[30:33]
	v_mfma_f32_16x16x32_bf16 v[26:29], v[144:147], v[184:187], v[26:29]
	v_mfma_f32_16x16x32_bf16 v[14:17], v[136:139], v[192:195], v[14:17]
	v_mfma_f32_16x16x32_bf16 v[10:13], v[144:147], v[192:195], v[10:13]
	v_mfma_f32_16x16x32_bf16 v[62:65], v[140:143], v[172:175], v[62:65]
	v_mfma_f32_16x16x32_bf16 v[58:61], v[148:151], v[172:175], v[58:61]
	v_mfma_f32_16x16x32_bf16 v[46:49], v[140:143], v[180:183], v[46:49]
	v_mfma_f32_16x16x32_bf16 v[42:45], v[148:151], v[180:183], v[42:45]
	v_mfma_f32_16x16x32_bf16 v[30:33], v[140:143], v[188:191], v[30:33]
	v_mfma_f32_16x16x32_bf16 v[26:29], v[148:151], v[188:191], v[26:29]
	v_mfma_f32_16x16x32_bf16 v[14:17], v[140:143], v[196:199], v[14:17]
	v_mfma_f32_16x16x32_bf16 v[10:13], v[148:151], v[196:199], v[10:13]
	s_barrier
	s_add_u32 s68, s50, 0x80000
	s_addc_u32 s69, s51, 0
	s_add_i32 s70, s70, s54
	s_mov_b32 m0, s70
	s_nop 0
	global_load_lds_dwordx4 v0, s[68:69]
	s_add_i32 m0, s70, 0x2000
	s_nop 0
	global_load_lds_dwordx4 v130, s[68:69]
	s_waitcnt vmcnt(6)
	s_barrier
	v_mfma_f32_16x16x32_bf16 v[54:57], v[224:227], v[168:171], v[54:57]
	v_mfma_f32_16x16x32_bf16 v[50:53], v[232:235], v[168:171], v[50:53]
	v_mfma_f32_16x16x32_bf16 v[38:41], v[224:227], v[176:179], v[38:41]
	v_mfma_f32_16x16x32_bf16 v[34:37], v[232:235], v[176:179], v[34:37]
	v_mfma_f32_16x16x32_bf16 v[22:25], v[224:227], v[184:187], v[22:25]
	v_mfma_f32_16x16x32_bf16 v[18:21], v[232:235], v[184:187], v[18:21]
	v_mfma_f32_16x16x32_bf16 v[6:9], v[224:227], v[192:195], v[6:9]
	v_mfma_f32_16x16x32_bf16 v[2:5], v[232:235], v[192:195], v[2:5]
	v_mfma_f32_16x16x32_bf16 v[54:57], v[228:231], v[172:175], v[54:57]
	v_mfma_f32_16x16x32_bf16 v[50:53], v[236:239], v[172:175], v[50:53]
	v_mfma_f32_16x16x32_bf16 v[38:41], v[228:231], v[180:183], v[38:41]
	v_mfma_f32_16x16x32_bf16 v[34:37], v[236:239], v[180:183], v[34:37]
	v_mfma_f32_16x16x32_bf16 v[22:25], v[228:231], v[188:191], v[22:25]
	v_mfma_f32_16x16x32_bf16 v[18:21], v[236:239], v[188:191], v[18:21]
	v_mfma_f32_16x16x32_bf16 v[6:9], v[228:231], v[196:199], v[6:9]
	v_mfma_f32_16x16x32_bf16 v[2:5], v[236:239], v[196:199], v[2:5]
	s_add_i32 s68, 0, 0x18000
	v_add_u32_e32 v148, s68, v153
	s_barrier
	ds_read_b128 v[136:139], v148
	ds_read_b128 v[140:143], v148 offset:1024
	ds_read_b128 v[144:147], v148 offset:2048
	ds_read_b128 v[148:151], v148 offset:3072
	s_add_u32 s52, s52, 0x80000
	s_addc_u32 s53, s53, 0
	s_mov_b32 m0, s57
	ds_read_b128 v[168:171], v155 offset:32768
	ds_read_b128 v[172:175], v155 offset:33792
	ds_read_b128 v[176:179], v155 offset:34816
	ds_read_b128 v[180:183], v155 offset:35840
	ds_read_b128 v[184:187], v155 offset:36864
	ds_read_b128 v[188:191], v155 offset:37888
	ds_read_b128 v[192:195], v155 offset:38912
	ds_read_b128 v[196:199], v155 offset:39936
	global_load_lds_dwordx4 v0, s[52:53]
	s_mov_b32 m0, s58
	s_nop 0
	global_load_lds_dwordx4 v130, s[52:53]
	s_waitcnt lgkmcnt(8)
	s_barrier
	s_waitcnt lgkmcnt(0)
	s_waitcnt lgkmcnt(0)
	v_mfma_f32_16x16x32_bf16 v[126:129], v[136:139], v[168:171], v[126:129]
	v_mfma_f32_16x16x32_bf16 v[122:125], v[144:147], v[168:171], v[122:125]
	v_mfma_f32_16x16x32_bf16 v[110:113], v[136:139], v[176:179], v[110:113]
	v_mfma_f32_16x16x32_bf16 v[106:109], v[144:147], v[176:179], v[106:109]
	v_mfma_f32_16x16x32_bf16 v[94:97], v[136:139], v[184:187], v[94:97]
	v_mfma_f32_16x16x32_bf16 v[90:93], v[144:147], v[184:187], v[90:93]
	v_mfma_f32_16x16x32_bf16 v[78:81], v[136:139], v[192:195], v[78:81]
	v_mfma_f32_16x16x32_bf16 v[74:77], v[144:147], v[192:195], v[74:77]
	v_mfma_f32_16x16x32_bf16 v[126:129], v[140:143], v[172:175], v[126:129]
	v_mfma_f32_16x16x32_bf16 v[122:125], v[148:151], v[172:175], v[122:125]
	v_mfma_f32_16x16x32_bf16 v[110:113], v[140:143], v[180:183], v[110:113]
	v_mfma_f32_16x16x32_bf16 v[106:109], v[148:151], v[180:183], v[106:109]
	v_mfma_f32_16x16x32_bf16 v[94:97], v[140:143], v[188:191], v[94:97]
	v_mfma_f32_16x16x32_bf16 v[90:93], v[148:151], v[188:191], v[90:93]
	v_mfma_f32_16x16x32_bf16 v[78:81], v[140:143], v[196:199], v[78:81]
	v_mfma_f32_16x16x32_bf16 v[74:77], v[148:151], v[196:199], v[74:77]
	s_barrier
	s_add_i32 s52, 0, 0x1c000
	s_add_i32 s53, s68, s54
	v_add_u32_e32 v161, s52, v153
	s_mov_b32 m0, s53
	ds_read_b128 v[224:227], v161
	ds_read_b128 v[228:231], v161 offset:1024
	ds_read_b128 v[232:235], v161 offset:2048
	ds_read_b128 v[236:239], v161 offset:3072
	global_load_lds_dwordx4 v0, s[76:77]
	s_add_i32 m0, s53, 0x2000
	s_nop 0
	global_load_lds_dwordx4 v130, s[76:77]
	s_barrier
	s_waitcnt lgkmcnt(0)
	s_waitcnt lgkmcnt(0)
	v_mfma_f32_16x16x32_bf16 v[118:121], v[224:227], v[168:171], v[118:121]
	v_mfma_f32_16x16x32_bf16 v[114:117], v[232:235], v[168:171], v[114:117]
	v_mfma_f32_16x16x32_bf16 v[102:105], v[224:227], v[176:179], v[102:105]
	v_mfma_f32_16x16x32_bf16 v[98:101], v[232:235], v[176:179], v[98:101]
	v_mfma_f32_16x16x32_bf16 v[86:89], v[224:227], v[184:187], v[86:89]
	v_mfma_f32_16x16x32_bf16 v[82:85], v[232:235], v[184:187], v[82:85]
	v_mfma_f32_16x16x32_bf16 v[70:73], v[224:227], v[192:195], v[70:73]
	v_mfma_f32_16x16x32_bf16 v[66:69], v[232:235], v[192:195], v[66:69]
	v_mfma_f32_16x16x32_bf16 v[118:121], v[228:231], v[172:175], v[118:121]
	v_mfma_f32_16x16x32_bf16 v[114:117], v[236:239], v[172:175], v[114:117]
	v_mfma_f32_16x16x32_bf16 v[102:105], v[228:231], v[180:183], v[102:105]
	v_mfma_f32_16x16x32_bf16 v[98:101], v[236:239], v[180:183], v[98:101]
	v_mfma_f32_16x16x32_bf16 v[86:89], v[228:231], v[188:191], v[86:89]
	v_mfma_f32_16x16x32_bf16 v[82:85], v[236:239], v[188:191], v[82:85]
	v_mfma_f32_16x16x32_bf16 v[70:73], v[228:231], v[196:199], v[70:73]
	v_mfma_f32_16x16x32_bf16 v[66:69], v[236:239], v[196:199], v[66:69]
	s_mov_b32 m0, s59
	s_barrier
	ds_read_b128 v[168:171], v155 offset:49152
	ds_read_b128 v[172:175], v155 offset:50176
	ds_read_b128 v[176:179], v155 offset:51200
	ds_read_b128 v[180:183], v155 offset:52224
	ds_read_b128 v[184:187], v155 offset:53248
	ds_read_b128 v[188:191], v155 offset:54272
	ds_read_b128 v[192:195], v155 offset:55296
	ds_read_b128 v[196:199], v155 offset:56320
	global_load_lds_dwordx4 v0, s[78:79]
	s_mov_b32 m0, s60
	s_nop 0
	global_load_lds_dwordx4 v130, s[78:79]
	s_barrier
	s_waitcnt lgkmcnt(0)
	s_waitcnt lgkmcnt(0)
	v_mfma_f32_16x16x32_bf16 v[62:65], v[136:139], v[168:171], v[62:65]
	v_mfma_f32_16x16x32_bf16 v[58:61], v[144:147], v[168:171], v[58:61]
	v_mfma_f32_16x16x32_bf16 v[46:49], v[136:139], v[176:179], v[46:49]
	v_mfma_f32_16x16x32_bf16 v[42:45], v[144:147], v[176:179], v[42:45]
	v_mfma_f32_16x16x32_bf16 v[30:33], v[136:139], v[184:187], v[30:33]
	v_mfma_f32_16x16x32_bf16 v[26:29], v[144:147], v[184:187], v[26:29]
	v_mfma_f32_16x16x32_bf16 v[14:17], v[136:139], v[192:195], v[14:17]
	v_mfma_f32_16x16x32_bf16 v[10:13], v[144:147], v[192:195], v[10:13]
	v_mfma_f32_16x16x32_bf16 v[62:65], v[140:143], v[172:175], v[62:65]
	v_mfma_f32_16x16x32_bf16 v[58:61], v[148:151], v[172:175], v[58:61]
	v_mfma_f32_16x16x32_bf16 v[46:49], v[140:143], v[180:183], v[46:49]
	v_mfma_f32_16x16x32_bf16 v[42:45], v[148:151], v[180:183], v[42:45]
	v_mfma_f32_16x16x32_bf16 v[30:33], v[140:143], v[188:191], v[30:33]
	v_mfma_f32_16x16x32_bf16 v[26:29], v[148:151], v[188:191], v[26:29]
	v_mfma_f32_16x16x32_bf16 v[14:17], v[140:143], v[196:199], v[14:17]
	v_mfma_f32_16x16x32_bf16 v[10:13], v[148:151], v[196:199], v[10:13]
	s_barrier
	s_add_u32 s50, s50, 0x80080
	s_addc_u32 s51, s51, 0
	s_add_i32 s52, s52, s54
	s_mov_b32 m0, s52
	s_nop 0
	global_load_lds_dwordx4 v0, s[50:51]
	s_add_i32 m0, s52, 0x2000
	s_nop 0
	global_load_lds_dwordx4 v130, s[50:51]
	s_waitcnt vmcnt(6)
	s_barrier
	v_mfma_f32_16x16x32_bf16 v[54:57], v[224:227], v[168:171], v[54:57]
	v_mfma_f32_16x16x32_bf16 v[50:53], v[232:235], v[168:171], v[50:53]
	v_mfma_f32_16x16x32_bf16 v[38:41], v[224:227], v[176:179], v[38:41]
	v_mfma_f32_16x16x32_bf16 v[34:37], v[232:235], v[176:179], v[34:37]
	v_mfma_f32_16x16x32_bf16 v[22:25], v[224:227], v[184:187], v[22:25]
	v_mfma_f32_16x16x32_bf16 v[18:21], v[232:235], v[184:187], v[18:21]
	v_mfma_f32_16x16x32_bf16 v[6:9], v[224:227], v[192:195], v[6:9]
	v_mfma_f32_16x16x32_bf16 v[2:5], v[232:235], v[192:195], v[2:5]
	v_mfma_f32_16x16x32_bf16 v[54:57], v[228:231], v[172:175], v[54:57]
	v_mfma_f32_16x16x32_bf16 v[50:53], v[236:239], v[172:175], v[50:53]
	v_mfma_f32_16x16x32_bf16 v[38:41], v[228:231], v[180:183], v[38:41]
	v_mfma_f32_16x16x32_bf16 v[34:37], v[236:239], v[180:183], v[34:37]
	v_mfma_f32_16x16x32_bf16 v[22:25], v[228:231], v[188:191], v[22:25]
	v_mfma_f32_16x16x32_bf16 v[18:21], v[236:239], v[188:191], v[18:21]
	v_mfma_f32_16x16x32_bf16 v[6:9], v[228:231], v[196:199], v[6:9]
	v_mfma_f32_16x16x32_bf16 v[2:5], v[236:239], v[196:199], v[2:5]
	s_add_u32 s0, s0, 0x100
	s_addc_u32 s1, s1, 0
	s_add_u32 s13, s13, 0x100
	s_addc_u32 s66, s66, 0
	s_cmp_ge_i32 s67, s41
	s_mov_b32 s50, s67
	s_barrier
	s_cbranch_scc0 .LBB0_282
	s_cmp_eq_u32 s63, 2
	s_cbranch_scc1 .Lepi6_orig
	v_readlane_b32 s90, v255, 17
	v_readlane_b32 s91, v255, 18
	v_readlane_b32 s96, v255, 19
	v_readlane_b32 s97, v255, 20
	v_readlane_b32 s8, v255, 25
	v_readlane_b32 s9, v255, 26
	v_readlane_b32 s68, v253, 58
	v_readlane_b32 s69, v253, 59
	v_lshl_or_b32 v156, s64, 8, v154
	v_lshlrev_b32_e32 v156, 2, v156
	v_lshl_add_u32 v157, v152, 13, v156
	s_lshl_b32 s72, s65, 21
	s_add_u32 s74, s68, s72
	s_addc_u32 s75, s69, 0
	s_add_u32 s76, s22, s72
	s_addc_u32 s77, s23, 0
	s_lshr_b32 s73, s65, 3
	s_mul_i32 s73, s73, 0xc000
	s_add_u32 s73, s73, 0x4000
	s_add_u32 s70, s90, s73
	s_addc_u32 s71, s91, 0
	global_load_dwordx4 v[140:143], v156, s[70:71]
	global_load_dwordx4 v[144:147], v156, s[70:71] offset:64
	global_load_dwordx4 v[148:151], v156, s[70:71] offset:512
	global_load_dwordx4 v[168:171], v156, s[70:71] offset:576
	global_load_dwordx4 v[224:227], v157, s[74:75] nt
	global_load_dwordx4 v[228:231], v157, s[74:75] offset:64 nt
	global_load_dwordx4 v[232:235], v157, s[74:75] offset:512 nt
	global_load_dwordx4 v[236:239], v157, s[74:75] offset:576 nt
	s_add_u32 s74, s74, 0x20000
	s_addc_u32 s75, s75, 0
	global_load_dwordx4 v[240:243], v157, s[74:75] nt
	global_load_dwordx4 v[244:247], v157, s[74:75] offset:64 nt
	s_waitcnt vmcnt(5)
	v_pk_fma_f32 v[128:129], v[128:129], v[142:143], v[226:227]
	v_pk_fma_f32 v[126:127], v[126:127], v[140:141], v[224:225]
	global_store_dwordx4 v157, v[126:129], s[76:77]
	global_load_dwordx4 v[224:227], v157, s[74:75] offset:512 nt
	s_waitcnt vmcnt(6)
	v_pk_fma_f32 v[124:125], v[124:125], v[146:147], v[230:231]
	v_pk_fma_f32 v[122:123], v[122:123], v[144:145], v[228:229]
	global_store_dwordx4 v157, v[122:125], s[76:77] offset:64
	global_load_dwordx4 v[228:231], v157, s[74:75] offset:576 nt
	s_waitcnt vmcnt(7)
	v_pk_fma_f32 v[120:121], v[120:121], v[150:151], v[234:235]
	v_pk_fma_f32 v[118:119], v[118:119], v[148:149], v[232:233]
	global_store_dwordx4 v157, v[118:121], s[76:77] offset:512
	s_add_u32 s74, s74, 0x20000
	s_addc_u32 s75, s75, 0
	global_load_dwordx4 v[232:235], v157, s[74:75] nt
	s_waitcnt vmcnt(8)
	v_pk_fma_f32 v[116:117], v[116:117], v[170:171], v[238:239]
	v_pk_fma_f32 v[114:115], v[114:115], v[168:169], v[236:237]
	global_store_dwordx4 v157, v[114:117], s[76:77] offset:576
	global_load_dwordx4 v[236:239], v157, s[74:75] offset:64 nt
	s_add_u32 s76, s76, 0x20000
	s_addc_u32 s77, s77, 0
	s_waitcnt vmcnt(9)
	v_pk_fma_f32 v[112:113], v[112:113], v[142:143], v[242:243]
	v_pk_fma_f32 v[110:111], v[110:111], v[140:141], v[240:241]
	global_store_dwordx4 v157, v[110:113], s[76:77]
	global_load_dwordx4 v[240:243], v157, s[74:75] offset:512 nt
	s_waitcnt vmcnt(10)
	v_pk_fma_f32 v[108:109], v[108:109], v[146:147], v[246:247]
	v_pk_fma_f32 v[106:107], v[106:107], v[144:145], v[244:245]
	global_store_dwordx4 v157, v[106:109], s[76:77] offset:64
	global_load_dwordx4 v[244:247], v157, s[74:75] offset:576 nt
	s_waitcnt vmcnt(10)
	v_pk_fma_f32 v[104:105], v[104:105], v[150:151], v[226:227]
	v_pk_fma_f32 v[102:103], v[102:103], v[148:149], v[224:225]
	global_store_dwordx4 v157, v[102:105], s[76:77] offset:512
	s_add_u32 s74, s74, 0x20000
	s_addc_u32 s75, s75, 0
	global_load_dwordx4 v[224:227], v157, s[74:75] nt
	s_waitcnt vmcnt(10)
	v_pk_fma_f32 v[100:101], v[100:101], v[170:171], v[230:231]
	v_pk_fma_f32 v[98:99], v[98:99], v[168:169], v[228:229]
	global_store_dwordx4 v157, v[98:101], s[76:77] offset:576
	global_load_dwordx4 v[228:231], v157, s[74:75] offset:64 nt
	s_add_u32 s76, s76, 0x20000
	s_addc_u32 s77, s77, 0
	s_waitcnt vmcnt(10)
	v_pk_fma_f32 v[96:97], v[96:97], v[142:143], v[234:235]
	v_pk_fma_f32 v[94:95], v[94:95], v[140:141], v[232:233]
	global_store_dwordx4 v157, v[94:97], s[76:77]
	global_load_dwordx4 v[232:235], v157, s[74:75] offset:512 nt
	s_waitcnt vmcnt(10)
	v_pk_fma_f32 v[92:93], v[92:93], v[146:147], v[238:239]
	v_pk_fma_f32 v[90:91], v[90:91], v[144:145], v[236:237]
	global_store_dwordx4 v157, v[90:93], s[76:77] offset:64
	global_load_dwordx4 v[236:239], v157, s[74:75] offset:576 nt
	s_waitcnt vmcnt(10)
	v_pk_fma_f32 v[88:89], v[88:89], v[150:151], v[242:243]
	v_pk_fma_f32 v[86:87], v[86:87], v[148:149], v[240:241]
	global_store_dwordx4 v157, v[86:89], s[76:77] offset:512
	s_add_u32 s74, s74, 0xa0000
	s_addc_u32 s75, s75, 0
	global_load_dwordx4 v[240:243], v157, s[74:75] nt
	s_waitcnt vmcnt(10)
	v_pk_fma_f32 v[84:85], v[84:85], v[170:171], v[246:247]
	v_pk_fma_f32 v[82:83], v[82:83], v[168:169], v[244:245]
	global_store_dwordx4 v157, v[82:85], s[76:77] offset:576
	global_load_dwordx4 v[244:247], v157, s[74:75] offset:64 nt
	s_add_u32 s76, s76, 0x20000
	s_addc_u32 s77, s77, 0
	s_waitcnt vmcnt(10)
	v_pk_fma_f32 v[80:81], v[80:81], v[142:143], v[226:227]
	v_pk_fma_f32 v[78:79], v[78:79], v[140:141], v[224:225]
	global_store_dwordx4 v157, v[78:81], s[76:77]
	global_load_dwordx4 v[224:227], v157, s[74:75] offset:512 nt
	s_waitcnt vmcnt(10)
	v_pk_fma_f32 v[76:77], v[76:77], v[146:147], v[230:231]
	v_pk_fma_f32 v[74:75], v[74:75], v[144:145], v[228:229]
	global_store_dwordx4 v157, v[74:77], s[76:77] offset:64
	global_load_dwordx4 v[228:231], v157, s[74:75] offset:576 nt
	s_waitcnt vmcnt(10)
	v_pk_fma_f32 v[72:73], v[72:73], v[150:151], v[234:235]
	v_pk_fma_f32 v[70:71], v[70:71], v[148:149], v[232:233]
	global_store_dwordx4 v157, v[70:73], s[76:77] offset:512
	s_add_u32 s74, s74, 0x20000
	s_addc_u32 s75, s75, 0
	global_load_dwordx4 v[232:235], v157, s[74:75] nt
	s_waitcnt vmcnt(10)
	v_pk_fma_f32 v[68:69], v[68:69], v[170:171], v[238:239]
	v_pk_fma_f32 v[66:67], v[66:67], v[168:169], v[236:237]
	global_store_dwordx4 v157, v[66:69], s[76:77] offset:576
	global_load_dwordx4 v[236:239], v157, s[74:75] offset:64 nt
	s_add_u32 s76, s76, 0xa0000
	s_addc_u32 s77, s77, 0
	s_waitcnt vmcnt(10)
	v_pk_fma_f32 v[64:65], v[64:65], v[142:143], v[242:243]
	v_pk_fma_f32 v[62:63], v[62:63], v[140:141], v[240:241]
	global_store_dwordx4 v157, v[62:65], s[76:77]
	global_load_dwordx4 v[240:243], v157, s[74:75] offset:512 nt
	s_waitcnt vmcnt(10)
	v_pk_fma_f32 v[60:61], v[60:61], v[146:147], v[246:247]
	v_pk_fma_f32 v[58:59], v[58:59], v[144:145], v[244:245]
	global_store_dwordx4 v157, v[58:61], s[76:77] offset:64
	global_load_dwordx4 v[244:247], v157, s[74:75] offset:576 nt
	s_waitcnt vmcnt(10)
	v_pk_fma_f32 v[56:57], v[56:57], v[150:151], v[226:227]
	v_pk_fma_f32 v[54:55], v[54:55], v[148:149], v[224:225]
	global_store_dwordx4 v157, v[54:57], s[76:77] offset:512
	s_add_u32 s74, s74, 0x20000
	s_addc_u32 s75, s75, 0
	global_load_dwordx4 v[224:227], v157, s[74:75] nt
	s_waitcnt vmcnt(10)
	v_pk_fma_f32 v[52:53], v[52:53], v[170:171], v[230:231]
	v_pk_fma_f32 v[50:51], v[50:51], v[168:169], v[228:229]
	global_store_dwordx4 v157, v[50:53], s[76:77] offset:576
	global_load_dwordx4 v[228:231], v157, s[74:75] offset:64 nt
	s_add_u32 s76, s76, 0x20000
	s_addc_u32 s77, s77, 0
	s_waitcnt vmcnt(10)
	v_pk_fma_f32 v[48:49], v[48:49], v[142:143], v[234:235]
	v_pk_fma_f32 v[46:47], v[46:47], v[140:141], v[232:233]
	global_store_dwordx4 v157, v[46:49], s[76:77]
	global_load_dwordx4 v[232:235], v157, s[74:75] offset:512 nt
	s_waitcnt vmcnt(10)
	v_pk_fma_f32 v[44:45], v[44:45], v[146:147], v[238:239]
	v_pk_fma_f32 v[42:43], v[42:43], v[144:145], v[236:237]
	global_store_dwordx4 v157, v[42:45], s[76:77] offset:64
	global_load_dwordx4 v[236:239], v157, s[74:75] offset:576 nt
	s_waitcnt vmcnt(10)
	v_pk_fma_f32 v[40:41], v[40:41], v[150:151], v[242:243]
	v_pk_fma_f32 v[38:39], v[38:39], v[148:149], v[240:241]
	global_store_dwordx4 v157, v[38:41], s[76:77] offset:512
	s_add_u32 s74, s74, 0x20000
	s_addc_u32 s75, s75, 0
	global_load_dwordx4 v[240:243], v157, s[74:75] nt
	s_waitcnt vmcnt(10)
	v_pk_fma_f32 v[36:37], v[36:37], v[170:171], v[246:247]
	v_pk_fma_f32 v[34:35], v[34:35], v[168:169], v[244:245]
	global_store_dwordx4 v157, v[34:37], s[76:77] offset:576
	global_load_dwordx4 v[244:247], v157, s[74:75] offset:64 nt
	s_add_u32 s76, s76, 0x20000
	s_addc_u32 s77, s77, 0
	s_waitcnt vmcnt(10)
	v_pk_fma_f32 v[32:33], v[32:33], v[142:143], v[226:227]
	v_pk_fma_f32 v[30:31], v[30:31], v[140:141], v[224:225]
	global_store_dwordx4 v157, v[30:33], s[76:77]
	global_load_dwordx4 v[224:227], v157, s[74:75] offset:512 nt
	s_waitcnt vmcnt(10)
	v_pk_fma_f32 v[28:29], v[28:29], v[146:147], v[230:231]
	v_pk_fma_f32 v[26:27], v[26:27], v[144:145], v[228:229]
	global_store_dwordx4 v157, v[26:29], s[76:77] offset:64
	global_load_dwordx4 v[228:231], v157, s[74:75] offset:576 nt
	s_waitcnt vmcnt(10)
	v_pk_fma_f32 v[24:25], v[24:25], v[150:151], v[234:235]
	v_pk_fma_f32 v[22:23], v[22:23], v[148:149], v[232:233]
	global_store_dwordx4 v157, v[22:25], s[76:77] offset:512
	s_waitcnt vmcnt(9)
	v_pk_fma_f32 v[20:21], v[20:21], v[170:171], v[238:239]
	v_pk_fma_f32 v[18:19], v[18:19], v[168:169], v[236:237]
	global_store_dwordx4 v157, v[18:21], s[76:77] offset:576
	s_add_u32 s76, s76, 0x20000
	s_addc_u32 s77, s77, 0
	s_waitcnt vmcnt(8)
	v_pk_fma_f32 v[16:17], v[16:17], v[142:143], v[242:243]
	v_pk_fma_f32 v[14:15], v[14:15], v[140:141], v[240:241]
	global_store_dwordx4 v157, v[14:17], s[76:77]
	s_waitcnt vmcnt(7)
	v_pk_fma_f32 v[12:13], v[12:13], v[146:147], v[246:247]
	v_pk_fma_f32 v[10:11], v[10:11], v[144:145], v[244:245]
	global_store_dwordx4 v157, v[10:13], s[76:77] offset:64
	s_waitcnt vmcnt(6)
	v_pk_fma_f32 v[8:9], v[8:9], v[150:151], v[226:227]
	v_pk_fma_f32 v[6:7], v[6:7], v[148:149], v[224:225]
	global_store_dwordx4 v157, v[6:9], s[76:77] offset:512
	s_waitcnt vmcnt(5)
	v_pk_fma_f32 v[4:5], v[4:5], v[170:171], v[230:231]
	v_pk_fma_f32 v[2:3], v[2:3], v[168:169], v[228:229]
	global_store_dwordx4 v157, v[2:5], s[76:77] offset:576
	s_branch .LBB0_269

.LBB0_572:
	s_add_u32 s41, s46, 0xfff80080
	s_addc_u32 s48, s47, -1
	s_add_i32 s64, 0, 0x10000
	v_add_u32_e32 v156, s64, v141
	ds_read_b128 v[144:147], v156
	ds_read_b128 v[148:151], v156 offset:1024
	ds_read_b128 v[152:155], v156 offset:2048
	ds_read_b128 v[168:171], v156 offset:3072
	s_cmp_eq_u32 s39, 28
	s_cselect_b32 s51, s43, s48
	s_cselect_b32 s50, s42, s41
	s_cselect_b32 s49, s45, s13
	s_cselect_b32 s48, s44, s12
	s_add_i32 m0, s54, 0xc000
	ds_read_b128 v[172:175], v143
	ds_read_b128 v[176:179], v143 offset:1024
	ds_read_b128 v[180:183], v143 offset:2048
	ds_read_b128 v[184:187], v143 offset:3072
	ds_read_b128 v[188:191], v143 offset:4096
	ds_read_b128 v[192:195], v143 offset:5120
	ds_read_b128 v[196:199], v143 offset:6144
	ds_read_b128 v[224:227], v143 offset:7168
	global_load_lds_dwordx4 v136, s[46:47]
	s_add_i32 m0, s54, 0xe000
	s_nop 0
	global_load_lds_dwordx4 v138, s[46:47]
	s_waitcnt lgkmcnt(8)
	s_barrier
	s_waitcnt lgkmcnt(0)
	s_waitcnt lgkmcnt(0)
	v_mfma_f32_16x16x32_bf16 v[126:129], v[144:147], v[172:175], v[126:129]
	v_mfma_f32_16x16x32_bf16 v[122:125], v[152:155], v[172:175], v[122:125]
	v_mfma_f32_16x16x32_bf16 v[118:121], v[144:147], v[180:183], v[118:121]
	v_mfma_f32_16x16x32_bf16 v[114:117], v[152:155], v[180:183], v[114:117]
	v_mfma_f32_16x16x32_bf16 v[102:105], v[144:147], v[188:191], v[102:105]
	v_mfma_f32_16x16x32_bf16 v[98:101], v[152:155], v[188:191], v[98:101]
	v_mfma_f32_16x16x32_bf16 v[86:89], v[144:147], v[196:199], v[86:89]
	v_mfma_f32_16x16x32_bf16 v[82:85], v[152:155], v[196:199], v[82:85]
	v_mfma_f32_16x16x32_bf16 v[126:129], v[148:151], v[176:179], v[126:129]
	v_mfma_f32_16x16x32_bf16 v[122:125], v[168:171], v[176:179], v[122:125]
	v_mfma_f32_16x16x32_bf16 v[118:121], v[148:151], v[184:187], v[118:121]
	v_mfma_f32_16x16x32_bf16 v[114:117], v[168:171], v[184:187], v[114:117]
	v_mfma_f32_16x16x32_bf16 v[102:105], v[148:151], v[192:195], v[102:105]
	v_mfma_f32_16x16x32_bf16 v[98:101], v[168:171], v[192:195], v[98:101]
	v_mfma_f32_16x16x32_bf16 v[86:89], v[148:151], v[224:227], v[86:89]
	v_mfma_f32_16x16x32_bf16 v[82:85], v[168:171], v[224:227], v[82:85]
	s_barrier
	s_add_i32 s41, 0, 0x14000
	v_add_u32_e32 v156, s41, v141
	s_add_i32 s64, s64, s53
	ds_read_b128 v[228:231], v156
	ds_read_b128 v[232:235], v156 offset:1024
	ds_read_b128 v[236:239], v156 offset:2048
	ds_read_b128 v[240:243], v156 offset:3072
	s_add_u32 s76, s48, s94
	s_addc_u32 s77, s49, s95
	s_mov_b32 m0, s64
	s_nop 0
	global_load_lds_dwordx4 v0, s[48:49]
	s_add_i32 m0, s64, 0x2000
	s_nop 0
	global_load_lds_dwordx4 v134, s[48:49]
	s_barrier
	s_waitcnt lgkmcnt(0)
	s_waitcnt lgkmcnt(0)
	v_mfma_f32_16x16x32_bf16 v[110:113], v[228:231], v[172:175], v[110:113]
	v_mfma_f32_16x16x32_bf16 v[106:109], v[236:239], v[172:175], v[106:109]
	v_mfma_f32_16x16x32_bf16 v[94:97], v[228:231], v[180:183], v[94:97]
	v_mfma_f32_16x16x32_bf16 v[90:93], v[236:239], v[180:183], v[90:93]
	v_mfma_f32_16x16x32_bf16 v[78:81], v[228:231], v[188:191], v[78:81]
	v_mfma_f32_16x16x32_bf16 v[74:77], v[236:239], v[188:191], v[74:77]
	v_mfma_f32_16x16x32_bf16 v[70:73], v[228:231], v[196:199], v[70:73]
	v_mfma_f32_16x16x32_bf16 v[66:69], v[236:239], v[196:199], v[66:69]
	v_mfma_f32_16x16x32_bf16 v[110:113], v[232:235], v[176:179], v[110:113]
	v_mfma_f32_16x16x32_bf16 v[106:109], v[240:243], v[176:179], v[106:109]
	v_mfma_f32_16x16x32_bf16 v[94:97], v[232:235], v[184:187], v[94:97]
	v_mfma_f32_16x16x32_bf16 v[90:93], v[240:243], v[184:187], v[90:93]
	v_mfma_f32_16x16x32_bf16 v[78:81], v[232:235], v[192:195], v[78:81]
	v_mfma_f32_16x16x32_bf16 v[74:77], v[240:243], v[192:195], v[74:77]
	v_mfma_f32_16x16x32_bf16 v[70:73], v[232:235], v[224:227], v[70:73]
	v_mfma_f32_16x16x32_bf16 v[66:69], v[240:243], v[224:227], v[66:69]
	s_mov_b32 m0, s54
	s_add_u32 s78, s50, s94
	s_addc_u32 s79, s51, s95
	s_barrier
	ds_read_b128 v[172:175], v143 offset:16384
	ds_read_b128 v[176:179], v143 offset:17408
	ds_read_b128 v[180:183], v143 offset:18432
	ds_read_b128 v[184:187], v143 offset:19456
	ds_read_b128 v[188:191], v143 offset:20480
	ds_read_b128 v[192:195], v143 offset:21504
	ds_read_b128 v[196:199], v143 offset:22528
	ds_read_b128 v[224:227], v143 offset:23552
	global_load_lds_dwordx4 v130, s[50:51]
	s_mov_b32 m0, s55
	s_nop 0
	global_load_lds_dwordx4 v132, s[50:51]
	s_barrier
	s_waitcnt lgkmcnt(0)
	s_waitcnt lgkmcnt(0)
	v_mfma_f32_16x16x32_bf16 v[62:65], v[144:147], v[172:175], v[62:65]
	v_mfma_f32_16x16x32_bf16 v[58:61], v[152:155], v[172:175], v[58:61]
	v_mfma_f32_16x16x32_bf16 v[54:57], v[144:147], v[180:183], v[54:57]
	v_mfma_f32_16x16x32_bf16 v[50:53], v[152:155], v[180:183], v[50:53]
	v_mfma_f32_16x16x32_bf16 v[38:41], v[144:147], v[188:191], v[38:41]
	v_mfma_f32_16x16x32_bf16 v[34:37], v[152:155], v[188:191], v[34:37]
	v_mfma_f32_16x16x32_bf16 v[22:25], v[144:147], v[196:199], v[22:25]
	v_mfma_f32_16x16x32_bf16 v[18:21], v[152:155], v[196:199], v[18:21]
	v_mfma_f32_16x16x32_bf16 v[62:65], v[148:151], v[176:179], v[62:65]
	v_mfma_f32_16x16x32_bf16 v[58:61], v[168:171], v[176:179], v[58:61]
	v_mfma_f32_16x16x32_bf16 v[54:57], v[148:151], v[184:187], v[54:57]
	v_mfma_f32_16x16x32_bf16 v[50:53], v[168:171], v[184:187], v[50:53]
	v_mfma_f32_16x16x32_bf16 v[38:41], v[148:151], v[192:195], v[38:41]
	v_mfma_f32_16x16x32_bf16 v[34:37], v[168:171], v[192:195], v[34:37]
	v_mfma_f32_16x16x32_bf16 v[22:25], v[148:151], v[224:227], v[22:25]
	v_mfma_f32_16x16x32_bf16 v[18:21], v[168:171], v[224:227], v[18:21]
	s_barrier
	s_add_u32 s64, s48, 0x80000
	s_addc_u32 s65, s49, 0
	s_add_i32 s41, s41, s53
	s_mov_b32 m0, s41
	s_nop 0
	global_load_lds_dwordx4 v0, s[64:65]
	s_add_i32 m0, s41, 0x2000
	s_nop 0
	global_load_lds_dwordx4 v134, s[64:65]
	s_waitcnt vmcnt(6)
	s_barrier
	v_mfma_f32_16x16x32_bf16 v[46:49], v[228:231], v[172:175], v[46:49]
	v_mfma_f32_16x16x32_bf16 v[42:45], v[236:239], v[172:175], v[42:45]
	v_mfma_f32_16x16x32_bf16 v[30:33], v[228:231], v[180:183], v[30:33]
	v_mfma_f32_16x16x32_bf16 v[26:29], v[236:239], v[180:183], v[26:29]
	v_mfma_f32_16x16x32_bf16 v[14:17], v[228:231], v[188:191], v[14:17]
	v_mfma_f32_16x16x32_bf16 v[10:13], v[236:239], v[188:191], v[10:13]
	v_mfma_f32_16x16x32_bf16 v[6:9], v[228:231], v[196:199], v[6:9]
	v_mfma_f32_16x16x32_bf16 v[2:5], v[236:239], v[196:199], v[2:5]
	v_mfma_f32_16x16x32_bf16 v[46:49], v[232:235], v[176:179], v[46:49]
	v_mfma_f32_16x16x32_bf16 v[42:45], v[240:243], v[176:179], v[42:45]
	v_mfma_f32_16x16x32_bf16 v[30:33], v[232:235], v[184:187], v[30:33]
	v_mfma_f32_16x16x32_bf16 v[26:29], v[240:243], v[184:187], v[26:29]
	v_mfma_f32_16x16x32_bf16 v[14:17], v[232:235], v[192:195], v[14:17]
	v_mfma_f32_16x16x32_bf16 v[10:13], v[240:243], v[192:195], v[10:13]
	v_mfma_f32_16x16x32_bf16 v[6:9], v[232:235], v[224:227], v[6:9]
	v_mfma_f32_16x16x32_bf16 v[2:5], v[240:243], v[224:227], v[2:5]
	s_add_i32 s41, 0, 0x18000
	v_add_u32_e32 v161, s41, v141
	s_barrier
	ds_read_b128 v[144:147], v161
	ds_read_b128 v[148:151], v161 offset:1024
	ds_read_b128 v[152:155], v161 offset:2048
	ds_read_b128 v[168:171], v161 offset:3072
	s_add_u32 s50, s50, 0x80000
	s_addc_u32 s51, s51, 0
	s_mov_b32 m0, s56
	ds_read_b128 v[172:175], v143 offset:32768
	ds_read_b128 v[176:179], v143 offset:33792
	ds_read_b128 v[180:183], v143 offset:34816
	ds_read_b128 v[184:187], v143 offset:35840
	ds_read_b128 v[188:191], v143 offset:36864
	ds_read_b128 v[192:195], v143 offset:37888
	ds_read_b128 v[196:199], v143 offset:38912
	ds_read_b128 v[224:227], v143 offset:39936
	global_load_lds_dwordx4 v130, s[50:51]
	s_mov_b32 m0, s57
	s_nop 0
	global_load_lds_dwordx4 v132, s[50:51]
	s_waitcnt lgkmcnt(8)
	s_barrier
	s_waitcnt lgkmcnt(0)
	s_waitcnt lgkmcnt(0)
	v_mfma_f32_16x16x32_bf16 v[126:129], v[144:147], v[172:175], v[126:129]
	v_mfma_f32_16x16x32_bf16 v[122:125], v[152:155], v[172:175], v[122:125]
	v_mfma_f32_16x16x32_bf16 v[118:121], v[144:147], v[180:183], v[118:121]
	v_mfma_f32_16x16x32_bf16 v[114:117], v[152:155], v[180:183], v[114:117]
	v_mfma_f32_16x16x32_bf16 v[102:105], v[144:147], v[188:191], v[102:105]
	v_mfma_f32_16x16x32_bf16 v[98:101], v[152:155], v[188:191], v[98:101]
	v_mfma_f32_16x16x32_bf16 v[86:89], v[144:147], v[196:199], v[86:89]
	v_mfma_f32_16x16x32_bf16 v[82:85], v[152:155], v[196:199], v[82:85]
	v_mfma_f32_16x16x32_bf16 v[126:129], v[148:151], v[176:179], v[126:129]
	v_mfma_f32_16x16x32_bf16 v[122:125], v[168:171], v[176:179], v[122:125]
	v_mfma_f32_16x16x32_bf16 v[118:121], v[148:151], v[184:187], v[118:121]
	v_mfma_f32_16x16x32_bf16 v[114:117], v[168:171], v[184:187], v[114:117]
	v_mfma_f32_16x16x32_bf16 v[102:105], v[148:151], v[192:195], v[102:105]
	v_mfma_f32_16x16x32_bf16 v[98:101], v[168:171], v[192:195], v[98:101]
	v_mfma_f32_16x16x32_bf16 v[86:89], v[148:151], v[224:227], v[86:89]
	v_mfma_f32_16x16x32_bf16 v[82:85], v[168:171], v[224:227], v[82:85]
	s_barrier
	s_add_i32 s50, 0, 0x1c000
	s_add_i32 s41, s41, s53
	v_add_u32_e32 v161, s50, v141
	s_mov_b32 m0, s41
	ds_read_b128 v[228:231], v161
	ds_read_b128 v[232:235], v161 offset:1024
	ds_read_b128 v[236:239], v161 offset:2048
	ds_read_b128 v[240:243], v161 offset:3072
	global_load_lds_dwordx4 v0, s[76:77]
	s_add_i32 m0, s41, 0x2000
	s_nop 0
	global_load_lds_dwordx4 v134, s[76:77]
	s_barrier
	s_waitcnt lgkmcnt(0)
	s_waitcnt lgkmcnt(0)
	v_mfma_f32_16x16x32_bf16 v[110:113], v[228:231], v[172:175], v[110:113]
	v_mfma_f32_16x16x32_bf16 v[106:109], v[236:239], v[172:175], v[106:109]
	v_mfma_f32_16x16x32_bf16 v[94:97], v[228:231], v[180:183], v[94:97]
	v_mfma_f32_16x16x32_bf16 v[90:93], v[236:239], v[180:183], v[90:93]
	v_mfma_f32_16x16x32_bf16 v[78:81], v[228:231], v[188:191], v[78:81]
	v_mfma_f32_16x16x32_bf16 v[74:77], v[236:239], v[188:191], v[74:77]
	v_mfma_f32_16x16x32_bf16 v[70:73], v[228:231], v[196:199], v[70:73]
	v_mfma_f32_16x16x32_bf16 v[66:69], v[236:239], v[196:199], v[66:69]
	v_mfma_f32_16x16x32_bf16 v[110:113], v[232:235], v[176:179], v[110:113]
	v_mfma_f32_16x16x32_bf16 v[106:109], v[240:243], v[176:179], v[106:109]
	v_mfma_f32_16x16x32_bf16 v[94:97], v[232:235], v[184:187], v[94:97]
	v_mfma_f32_16x16x32_bf16 v[90:93], v[240:243], v[184:187], v[90:93]
	v_mfma_f32_16x16x32_bf16 v[78:81], v[232:235], v[192:195], v[78:81]
	v_mfma_f32_16x16x32_bf16 v[74:77], v[240:243], v[192:195], v[74:77]
	v_mfma_f32_16x16x32_bf16 v[70:73], v[232:235], v[224:227], v[70:73]
	v_mfma_f32_16x16x32_bf16 v[66:69], v[240:243], v[224:227], v[66:69]
	s_mov_b32 m0, s59
	s_barrier
	ds_read_b128 v[172:175], v143 offset:49152
	ds_read_b128 v[176:179], v143 offset:50176
	ds_read_b128 v[180:183], v143 offset:51200
	ds_read_b128 v[184:187], v143 offset:52224
	ds_read_b128 v[188:191], v143 offset:53248
	ds_read_b128 v[192:195], v143 offset:54272
	ds_read_b128 v[196:199], v143 offset:55296
	ds_read_b128 v[224:227], v143 offset:56320
	global_load_lds_dwordx4 v130, s[78:79]
	s_mov_b32 m0, s60
	s_nop 0
	global_load_lds_dwordx4 v132, s[78:79]
	s_barrier
	s_waitcnt lgkmcnt(0)
	s_waitcnt lgkmcnt(0)
	v_mfma_f32_16x16x32_bf16 v[62:65], v[144:147], v[172:175], v[62:65]
	v_mfma_f32_16x16x32_bf16 v[58:61], v[152:155], v[172:175], v[58:61]
	v_mfma_f32_16x16x32_bf16 v[54:57], v[144:147], v[180:183], v[54:57]
	v_mfma_f32_16x16x32_bf16 v[50:53], v[152:155], v[180:183], v[50:53]
	v_mfma_f32_16x16x32_bf16 v[38:41], v[144:147], v[188:191], v[38:41]
	v_mfma_f32_16x16x32_bf16 v[34:37], v[152:155], v[188:191], v[34:37]
	v_mfma_f32_16x16x32_bf16 v[22:25], v[144:147], v[196:199], v[22:25]
	v_mfma_f32_16x16x32_bf16 v[18:21], v[152:155], v[196:199], v[18:21]
	v_mfma_f32_16x16x32_bf16 v[62:65], v[148:151], v[176:179], v[62:65]
	v_mfma_f32_16x16x32_bf16 v[58:61], v[168:171], v[176:179], v[58:61]
	v_mfma_f32_16x16x32_bf16 v[54:57], v[148:151], v[184:187], v[54:57]
	v_mfma_f32_16x16x32_bf16 v[50:53], v[168:171], v[184:187], v[50:53]
	v_mfma_f32_16x16x32_bf16 v[38:41], v[148:151], v[192:195], v[38:41]
	v_mfma_f32_16x16x32_bf16 v[34:37], v[168:171], v[192:195], v[34:37]
	v_mfma_f32_16x16x32_bf16 v[22:25], v[148:151], v[224:227], v[22:25]
	v_mfma_f32_16x16x32_bf16 v[18:21], v[168:171], v[224:227], v[18:21]
	s_barrier
	s_add_u32 s48, s48, 0x80080
	s_addc_u32 s49, s49, 0
	s_add_i32 s41, s50, s53
	s_mov_b32 m0, s41
	s_nop 0
	global_load_lds_dwordx4 v0, s[48:49]
	s_add_i32 m0, s41, 0x2000
	s_nop 0
	global_load_lds_dwordx4 v134, s[48:49]
	s_waitcnt vmcnt(6)
	s_barrier
	v_mfma_f32_16x16x32_bf16 v[46:49], v[228:231], v[172:175], v[46:49]
	v_mfma_f32_16x16x32_bf16 v[42:45], v[236:239], v[172:175], v[42:45]
	v_mfma_f32_16x16x32_bf16 v[30:33], v[228:231], v[180:183], v[30:33]
	v_mfma_f32_16x16x32_bf16 v[26:29], v[236:239], v[180:183], v[26:29]
	v_mfma_f32_16x16x32_bf16 v[14:17], v[228:231], v[188:191], v[14:17]
	v_mfma_f32_16x16x32_bf16 v[10:13], v[236:239], v[188:191], v[10:13]
	v_mfma_f32_16x16x32_bf16 v[6:9], v[228:231], v[196:199], v[6:9]
	v_mfma_f32_16x16x32_bf16 v[2:5], v[236:239], v[196:199], v[2:5]
	v_mfma_f32_16x16x32_bf16 v[46:49], v[232:235], v[176:179], v[46:49]
	v_mfma_f32_16x16x32_bf16 v[42:45], v[240:243], v[176:179], v[42:45]
	v_mfma_f32_16x16x32_bf16 v[30:33], v[232:235], v[184:187], v[30:33]
	v_mfma_f32_16x16x32_bf16 v[26:29], v[240:243], v[184:187], v[26:29]
	v_mfma_f32_16x16x32_bf16 v[14:17], v[232:235], v[192:195], v[14:17]
	v_mfma_f32_16x16x32_bf16 v[10:13], v[240:243], v[192:195], v[10:13]
	v_mfma_f32_16x16x32_bf16 v[6:9], v[232:235], v[224:227], v[6:9]
	v_mfma_f32_16x16x32_bf16 v[2:5], v[240:243], v[224:227], v[2:5]
	s_add_i32 s39, s39, 2
	s_add_u32 s46, s46, 0x100
	s_addc_u32 s47, s47, 0
	s_add_u32 s12, s12, 0x100
	s_addc_u32 s13, s13, 0
	s_cmp_gt_u32 s39, 29
	s_barrier
	s_cbranch_scc0 .LBB0_572
	s_cmp_lg_u32 s62, 0
	s_cbranch_scc0 .LBB0_575
	s_lshl_b32 s39, s61, 8
	s_mov_b64 s[12:13], 0
	s_branch .LBB0_576

.LBB0_623:
	s_or_b64 exec, exec, s[0:1]
	s_movk_i32 s0, 0x3390
	v_mul_lo_u32 v0, v24, s0
	v_add_u32_e32 v130, 0, v0
	v_lshlrev_b32_e32 v0, 4, v166
	v_and_b32_e32 v82, 0xf0, v0
	v_readlane_b32 s0, v251, 19
	v_ashrrev_i32_e32 v133, 4, v166
	v_lshlrev_b32_e32 v0, 2, v82
	v_readlane_b32 s1, v251, 20
	v_cmp_eq_u32_e64 s[38:39], 0, v166
	v_and_b32_e32 v131, 31, v166
	v_lshl_add_u64 v[84:85], s[0:1], 0, v[0:1]
	v_mul_lo_u32 v0, v133, s93
	v_add_u32_e32 v0, 0, v0
	v_lshlrev_b32_e32 v2, 1, v82
	v_writelane_b32 v255, s38, 39
	v_lshrrev_b32_e32 v132, 5, v83
	v_and_b32_e32 v134, 15, v133
	v_cmp_lt_u32_e64 s[40:41], 63, v82
	v_cmp_lt_u32_e64 s[42:43], s46, v82
	v_mad_u32_u24 v135, v131, s93, 0
	v_lshlrev_b32_e32 v136, 1, v24
	v_lshlrev_b32_e32 v137, 3, v83
	v_add_u32_e32 v138, v0, v2
	v_writelane_b32 v255, s39, 40
	s_and_saveexec_b64 s[0:1], s[38:39]
	v_readlane_b32 s44, v251, 1
	v_readlane_b32 s45, v251, 2
	v_mov_b32_e32 v209, 1
	s_nop 3
	global_atomic_add v209, v1, v209, s[44:45] sc0
	s_or_b64 exec, exec, s[0:1]
	s_branch .LBB0_626

.LBB0_626:
	s_barrier
	s_and_saveexec_b64 s[0:1], s[38:39]
	s_cbranch_execz .LBB0_630
	v_readlane_b32 s12, v254, 40
	v_readlane_b32 s44, v251, 1
	v_readlane_b32 s45, v251, 2
	s_waitcnt vmcnt(0) lgkmcnt(0)
	v_mov_b32_e32 v2, s12
	v_mov_b32_e32 v0, v209
	ds_write_b32 v2, v0
	v_mov_b32_e32 v209, 1
	s_nop 1
	global_atomic_add v209, v1, v209, s[44:45] sc0

.LBB0_765:
	s_waitcnt vmcnt(0)
	s_mov_b64 s[0:1], 0

.LBB0_788:
	s_add_u32 s39, s46, 0xfff80080
	s_addc_u32 s48, s47, -1
	s_add_i32 s64, 0, 0x10000
	v_add_u32_e32 v156, s64, v141
	ds_read_b128 v[144:147], v156
	ds_read_b128 v[148:151], v156 offset:1024
	ds_read_b128 v[152:155], v156 offset:2048
	ds_read_b128 v[168:171], v156 offset:3072
	s_cmp_eq_u32 s13, 28
	s_cselect_b32 s51, s43, s48
	s_cselect_b32 s50, s42, s39
	s_cselect_b32 s49, s45, s12
	s_cselect_b32 s48, s44, s1
	s_add_i32 m0, s54, 0xc000
	ds_read_b128 v[172:175], v143
	ds_read_b128 v[176:179], v143 offset:1024
	ds_read_b128 v[180:183], v143 offset:2048
	ds_read_b128 v[184:187], v143 offset:3072
	ds_read_b128 v[188:191], v143 offset:4096
	ds_read_b128 v[192:195], v143 offset:5120
	ds_read_b128 v[196:199], v143 offset:6144
	ds_read_b128 v[224:227], v143 offset:7168
	global_load_lds_dwordx4 v136, s[46:47]
	s_add_i32 m0, s54, 0xe000
	s_nop 0
	global_load_lds_dwordx4 v138, s[46:47]
	s_waitcnt lgkmcnt(8)
	s_barrier
	s_waitcnt lgkmcnt(0)
	s_waitcnt lgkmcnt(0)
	v_mfma_f32_16x16x32_bf16 v[126:129], v[144:147], v[172:175], v[126:129]
	v_mfma_f32_16x16x32_bf16 v[122:125], v[152:155], v[172:175], v[122:125]
	v_mfma_f32_16x16x32_bf16 v[118:121], v[144:147], v[180:183], v[118:121]
	v_mfma_f32_16x16x32_bf16 v[114:117], v[152:155], v[180:183], v[114:117]
	v_mfma_f32_16x16x32_bf16 v[102:105], v[144:147], v[188:191], v[102:105]
	v_mfma_f32_16x16x32_bf16 v[98:101], v[152:155], v[188:191], v[98:101]
	v_mfma_f32_16x16x32_bf16 v[86:89], v[144:147], v[196:199], v[86:89]
	v_mfma_f32_16x16x32_bf16 v[82:85], v[152:155], v[196:199], v[82:85]
	v_mfma_f32_16x16x32_bf16 v[126:129], v[148:151], v[176:179], v[126:129]
	v_mfma_f32_16x16x32_bf16 v[122:125], v[168:171], v[176:179], v[122:125]
	v_mfma_f32_16x16x32_bf16 v[118:121], v[148:151], v[184:187], v[118:121]
	v_mfma_f32_16x16x32_bf16 v[114:117], v[168:171], v[184:187], v[114:117]
	v_mfma_f32_16x16x32_bf16 v[102:105], v[148:151], v[192:195], v[102:105]
	v_mfma_f32_16x16x32_bf16 v[98:101], v[168:171], v[192:195], v[98:101]
	v_mfma_f32_16x16x32_bf16 v[86:89], v[148:151], v[224:227], v[86:89]
	v_mfma_f32_16x16x32_bf16 v[82:85], v[168:171], v[224:227], v[82:85]
	s_barrier
	s_add_i32 s39, 0, 0x14000
	v_add_u32_e32 v156, s39, v141
	s_add_i32 s64, s64, s53
	ds_read_b128 v[228:231], v156
	ds_read_b128 v[232:235], v156 offset:1024
	ds_read_b128 v[236:239], v156 offset:2048
	ds_read_b128 v[240:243], v156 offset:3072
	s_add_u32 s76, s48, s94
	s_addc_u32 s77, s49, s95
	s_mov_b32 m0, s64
	s_nop 0
	global_load_lds_dwordx4 v0, s[48:49]
	s_add_i32 m0, s64, 0x2000
	s_nop 0
	global_load_lds_dwordx4 v134, s[48:49]
	s_barrier
	s_waitcnt lgkmcnt(0)
	s_waitcnt lgkmcnt(0)
	v_mfma_f32_16x16x32_bf16 v[110:113], v[228:231], v[172:175], v[110:113]
	v_mfma_f32_16x16x32_bf16 v[106:109], v[236:239], v[172:175], v[106:109]
	v_mfma_f32_16x16x32_bf16 v[94:97], v[228:231], v[180:183], v[94:97]
	v_mfma_f32_16x16x32_bf16 v[90:93], v[236:239], v[180:183], v[90:93]
	v_mfma_f32_16x16x32_bf16 v[78:81], v[228:231], v[188:191], v[78:81]
	v_mfma_f32_16x16x32_bf16 v[74:77], v[236:239], v[188:191], v[74:77]
	v_mfma_f32_16x16x32_bf16 v[70:73], v[228:231], v[196:199], v[70:73]
	v_mfma_f32_16x16x32_bf16 v[66:69], v[236:239], v[196:199], v[66:69]
	v_mfma_f32_16x16x32_bf16 v[110:113], v[232:235], v[176:179], v[110:113]
	v_mfma_f32_16x16x32_bf16 v[106:109], v[240:243], v[176:179], v[106:109]
	v_mfma_f32_16x16x32_bf16 v[94:97], v[232:235], v[184:187], v[94:97]
	v_mfma_f32_16x16x32_bf16 v[90:93], v[240:243], v[184:187], v[90:93]
	v_mfma_f32_16x16x32_bf16 v[78:81], v[232:235], v[192:195], v[78:81]
	v_mfma_f32_16x16x32_bf16 v[74:77], v[240:243], v[192:195], v[74:77]
	v_mfma_f32_16x16x32_bf16 v[70:73], v[232:235], v[224:227], v[70:73]
	v_mfma_f32_16x16x32_bf16 v[66:69], v[240:243], v[224:227], v[66:69]
	s_mov_b32 m0, s54
	s_add_u32 s78, s50, s94
	s_addc_u32 s79, s51, s95
	s_barrier
	ds_read_b128 v[172:175], v143 offset:16384
	ds_read_b128 v[176:179], v143 offset:17408
	ds_read_b128 v[180:183], v143 offset:18432
	ds_read_b128 v[184:187], v143 offset:19456
	ds_read_b128 v[188:191], v143 offset:20480
	ds_read_b128 v[192:195], v143 offset:21504
	ds_read_b128 v[196:199], v143 offset:22528
	ds_read_b128 v[224:227], v143 offset:23552
	global_load_lds_dwordx4 v130, s[50:51]
	s_mov_b32 m0, s55
	s_nop 0
	global_load_lds_dwordx4 v132, s[50:51]
	s_barrier
	s_waitcnt lgkmcnt(0)
	s_waitcnt lgkmcnt(0)
	v_mfma_f32_16x16x32_bf16 v[62:65], v[144:147], v[172:175], v[62:65]
	v_mfma_f32_16x16x32_bf16 v[58:61], v[152:155], v[172:175], v[58:61]
	v_mfma_f32_16x16x32_bf16 v[54:57], v[144:147], v[180:183], v[54:57]
	v_mfma_f32_16x16x32_bf16 v[50:53], v[152:155], v[180:183], v[50:53]
	v_mfma_f32_16x16x32_bf16 v[38:41], v[144:147], v[188:191], v[38:41]
	v_mfma_f32_16x16x32_bf16 v[34:37], v[152:155], v[188:191], v[34:37]
	v_mfma_f32_16x16x32_bf16 v[22:25], v[144:147], v[196:199], v[22:25]
	v_mfma_f32_16x16x32_bf16 v[18:21], v[152:155], v[196:199], v[18:21]
	v_mfma_f32_16x16x32_bf16 v[62:65], v[148:151], v[176:179], v[62:65]
	v_mfma_f32_16x16x32_bf16 v[58:61], v[168:171], v[176:179], v[58:61]
	v_mfma_f32_16x16x32_bf16 v[54:57], v[148:151], v[184:187], v[54:57]
	v_mfma_f32_16x16x32_bf16 v[50:53], v[168:171], v[184:187], v[50:53]
	v_mfma_f32_16x16x32_bf16 v[38:41], v[148:151], v[192:195], v[38:41]
	v_mfma_f32_16x16x32_bf16 v[34:37], v[168:171], v[192:195], v[34:37]
	v_mfma_f32_16x16x32_bf16 v[22:25], v[148:151], v[224:227], v[22:25]
	v_mfma_f32_16x16x32_bf16 v[18:21], v[168:171], v[224:227], v[18:21]
	s_barrier
	s_add_u32 s64, s48, 0x80000
	s_addc_u32 s65, s49, 0
	s_add_i32 s39, s39, s53
	s_mov_b32 m0, s39
	s_nop 0
	global_load_lds_dwordx4 v0, s[64:65]
	s_add_i32 m0, s39, 0x2000
	s_nop 0
	global_load_lds_dwordx4 v134, s[64:65]
	s_waitcnt vmcnt(6)
	s_barrier
	v_mfma_f32_16x16x32_bf16 v[46:49], v[228:231], v[172:175], v[46:49]
	v_mfma_f32_16x16x32_bf16 v[42:45], v[236:239], v[172:175], v[42:45]
	v_mfma_f32_16x16x32_bf16 v[30:33], v[228:231], v[180:183], v[30:33]
	v_mfma_f32_16x16x32_bf16 v[26:29], v[236:239], v[180:183], v[26:29]
	v_mfma_f32_16x16x32_bf16 v[14:17], v[228:231], v[188:191], v[14:17]
	v_mfma_f32_16x16x32_bf16 v[10:13], v[236:239], v[188:191], v[10:13]
	v_mfma_f32_16x16x32_bf16 v[6:9], v[228:231], v[196:199], v[6:9]
	v_mfma_f32_16x16x32_bf16 v[2:5], v[236:239], v[196:199], v[2:5]
	v_mfma_f32_16x16x32_bf16 v[46:49], v[232:235], v[176:179], v[46:49]
	v_mfma_f32_16x16x32_bf16 v[42:45], v[240:243], v[176:179], v[42:45]
	v_mfma_f32_16x16x32_bf16 v[30:33], v[232:235], v[184:187], v[30:33]
	v_mfma_f32_16x16x32_bf16 v[26:29], v[240:243], v[184:187], v[26:29]
	v_mfma_f32_16x16x32_bf16 v[14:17], v[232:235], v[192:195], v[14:17]
	v_mfma_f32_16x16x32_bf16 v[10:13], v[240:243], v[192:195], v[10:13]
	v_mfma_f32_16x16x32_bf16 v[6:9], v[232:235], v[224:227], v[6:9]
	v_mfma_f32_16x16x32_bf16 v[2:5], v[240:243], v[224:227], v[2:5]
	s_add_i32 s39, 0, 0x18000
	v_add_u32_e32 v161, s39, v141
	s_barrier
	ds_read_b128 v[144:147], v161
	ds_read_b128 v[148:151], v161 offset:1024
	ds_read_b128 v[152:155], v161 offset:2048
	ds_read_b128 v[168:171], v161 offset:3072
	s_add_u32 s50, s50, 0x80000
	s_addc_u32 s51, s51, 0
	s_mov_b32 m0, s56
	ds_read_b128 v[172:175], v143 offset:32768
	ds_read_b128 v[176:179], v143 offset:33792
	ds_read_b128 v[180:183], v143 offset:34816
	ds_read_b128 v[184:187], v143 offset:35840
	ds_read_b128 v[188:191], v143 offset:36864
	ds_read_b128 v[192:195], v143 offset:37888
	ds_read_b128 v[196:199], v143 offset:38912
	ds_read_b128 v[224:227], v143 offset:39936
	global_load_lds_dwordx4 v130, s[50:51]
	s_mov_b32 m0, s57
	s_nop 0
	global_load_lds_dwordx4 v132, s[50:51]
	s_waitcnt lgkmcnt(8)
	s_barrier
	s_waitcnt lgkmcnt(0)
	s_waitcnt lgkmcnt(0)
	v_mfma_f32_16x16x32_bf16 v[126:129], v[144:147], v[172:175], v[126:129]
	v_mfma_f32_16x16x32_bf16 v[122:125], v[152:155], v[172:175], v[122:125]
	v_mfma_f32_16x16x32_bf16 v[118:121], v[144:147], v[180:183], v[118:121]
	v_mfma_f32_16x16x32_bf16 v[114:117], v[152:155], v[180:183], v[114:117]
	v_mfma_f32_16x16x32_bf16 v[102:105], v[144:147], v[188:191], v[102:105]
	v_mfma_f32_16x16x32_bf16 v[98:101], v[152:155], v[188:191], v[98:101]
	v_mfma_f32_16x16x32_bf16 v[86:89], v[144:147], v[196:199], v[86:89]
	v_mfma_f32_16x16x32_bf16 v[82:85], v[152:155], v[196:199], v[82:85]
	v_mfma_f32_16x16x32_bf16 v[126:129], v[148:151], v[176:179], v[126:129]
	v_mfma_f32_16x16x32_bf16 v[122:125], v[168:171], v[176:179], v[122:125]
	v_mfma_f32_16x16x32_bf16 v[118:121], v[148:151], v[184:187], v[118:121]
	v_mfma_f32_16x16x32_bf16 v[114:117], v[168:171], v[184:187], v[114:117]
	v_mfma_f32_16x16x32_bf16 v[102:105], v[148:151], v[192:195], v[102:105]
	v_mfma_f32_16x16x32_bf16 v[98:101], v[168:171], v[192:195], v[98:101]
	v_mfma_f32_16x16x32_bf16 v[86:89], v[148:151], v[224:227], v[86:89]
	v_mfma_f32_16x16x32_bf16 v[82:85], v[168:171], v[224:227], v[82:85]
	s_barrier
	s_add_i32 s50, 0, 0x1c000
	s_add_i32 s39, s39, s53
	v_add_u32_e32 v161, s50, v141
	s_mov_b32 m0, s39
	ds_read_b128 v[228:231], v161
	ds_read_b128 v[232:235], v161 offset:1024
	ds_read_b128 v[236:239], v161 offset:2048
	ds_read_b128 v[240:243], v161 offset:3072
	global_load_lds_dwordx4 v0, s[76:77]
	s_add_i32 m0, s39, 0x2000
	s_nop 0
	global_load_lds_dwordx4 v134, s[76:77]
	s_barrier
	s_waitcnt lgkmcnt(0)
	s_waitcnt lgkmcnt(0)
	v_mfma_f32_16x16x32_bf16 v[110:113], v[228:231], v[172:175], v[110:113]
	v_mfma_f32_16x16x32_bf16 v[106:109], v[236:239], v[172:175], v[106:109]
	v_mfma_f32_16x16x32_bf16 v[94:97], v[228:231], v[180:183], v[94:97]
	v_mfma_f32_16x16x32_bf16 v[90:93], v[236:239], v[180:183], v[90:93]
	v_mfma_f32_16x16x32_bf16 v[78:81], v[228:231], v[188:191], v[78:81]
	v_mfma_f32_16x16x32_bf16 v[74:77], v[236:239], v[188:191], v[74:77]
	v_mfma_f32_16x16x32_bf16 v[70:73], v[228:231], v[196:199], v[70:73]
	v_mfma_f32_16x16x32_bf16 v[66:69], v[236:239], v[196:199], v[66:69]
	v_mfma_f32_16x16x32_bf16 v[110:113], v[232:235], v[176:179], v[110:113]
	v_mfma_f32_16x16x32_bf16 v[106:109], v[240:243], v[176:179], v[106:109]
	v_mfma_f32_16x16x32_bf16 v[94:97], v[232:235], v[184:187], v[94:97]
	v_mfma_f32_16x16x32_bf16 v[90:93], v[240:243], v[184:187], v[90:93]
	v_mfma_f32_16x16x32_bf16 v[78:81], v[232:235], v[192:195], v[78:81]
	v_mfma_f32_16x16x32_bf16 v[74:77], v[240:243], v[192:195], v[74:77]
	v_mfma_f32_16x16x32_bf16 v[70:73], v[232:235], v[224:227], v[70:73]
	v_mfma_f32_16x16x32_bf16 v[66:69], v[240:243], v[224:227], v[66:69]
	s_mov_b32 m0, s59
	s_barrier
	ds_read_b128 v[172:175], v143 offset:49152
	ds_read_b128 v[176:179], v143 offset:50176
	ds_read_b128 v[180:183], v143 offset:51200
	ds_read_b128 v[184:187], v143 offset:52224
	ds_read_b128 v[188:191], v143 offset:53248
	ds_read_b128 v[192:195], v143 offset:54272
	ds_read_b128 v[196:199], v143 offset:55296
	ds_read_b128 v[224:227], v143 offset:56320
	global_load_lds_dwordx4 v130, s[78:79]
	s_mov_b32 m0, s61
	s_nop 0
	global_load_lds_dwordx4 v132, s[78:79]
	s_barrier
	s_waitcnt lgkmcnt(0)
	s_waitcnt lgkmcnt(0)
	v_mfma_f32_16x16x32_bf16 v[62:65], v[144:147], v[172:175], v[62:65]
	v_mfma_f32_16x16x32_bf16 v[58:61], v[152:155], v[172:175], v[58:61]
	v_mfma_f32_16x16x32_bf16 v[54:57], v[144:147], v[180:183], v[54:57]
	v_mfma_f32_16x16x32_bf16 v[50:53], v[152:155], v[180:183], v[50:53]
	v_mfma_f32_16x16x32_bf16 v[38:41], v[144:147], v[188:191], v[38:41]
	v_mfma_f32_16x16x32_bf16 v[34:37], v[152:155], v[188:191], v[34:37]
	v_mfma_f32_16x16x32_bf16 v[22:25], v[144:147], v[196:199], v[22:25]
	v_mfma_f32_16x16x32_bf16 v[18:21], v[152:155], v[196:199], v[18:21]
	v_mfma_f32_16x16x32_bf16 v[62:65], v[148:151], v[176:179], v[62:65]
	v_mfma_f32_16x16x32_bf16 v[58:61], v[168:171], v[176:179], v[58:61]
	v_mfma_f32_16x16x32_bf16 v[54:57], v[148:151], v[184:187], v[54:57]
	v_mfma_f32_16x16x32_bf16 v[50:53], v[168:171], v[184:187], v[50:53]
	v_mfma_f32_16x16x32_bf16 v[38:41], v[148:151], v[192:195], v[38:41]
	v_mfma_f32_16x16x32_bf16 v[34:37], v[168:171], v[192:195], v[34:37]
	v_mfma_f32_16x16x32_bf16 v[22:25], v[148:151], v[224:227], v[22:25]
	v_mfma_f32_16x16x32_bf16 v[18:21], v[168:171], v[224:227], v[18:21]
	s_barrier
	s_add_u32 s48, s48, 0x80080
	s_addc_u32 s49, s49, 0
	s_add_i32 s39, s50, s53
	s_mov_b32 m0, s39
	s_nop 0
	global_load_lds_dwordx4 v0, s[48:49]
	s_add_i32 m0, s39, 0x2000
	s_nop 0
	global_load_lds_dwordx4 v134, s[48:49]
	s_waitcnt vmcnt(6)
	s_barrier
	v_mfma_f32_16x16x32_bf16 v[46:49], v[228:231], v[172:175], v[46:49]
	v_mfma_f32_16x16x32_bf16 v[42:45], v[236:239], v[172:175], v[42:45]
	v_mfma_f32_16x16x32_bf16 v[30:33], v[228:231], v[180:183], v[30:33]
	v_mfma_f32_16x16x32_bf16 v[26:29], v[236:239], v[180:183], v[26:29]
	v_mfma_f32_16x16x32_bf16 v[14:17], v[228:231], v[188:191], v[14:17]
	v_mfma_f32_16x16x32_bf16 v[10:13], v[236:239], v[188:191], v[10:13]
	v_mfma_f32_16x16x32_bf16 v[6:9], v[228:231], v[196:199], v[6:9]
	v_mfma_f32_16x16x32_bf16 v[2:5], v[236:239], v[196:199], v[2:5]
	v_mfma_f32_16x16x32_bf16 v[46:49], v[232:235], v[176:179], v[46:49]
	v_mfma_f32_16x16x32_bf16 v[42:45], v[240:243], v[176:179], v[42:45]
	v_mfma_f32_16x16x32_bf16 v[30:33], v[232:235], v[184:187], v[30:33]
	v_mfma_f32_16x16x32_bf16 v[26:29], v[240:243], v[184:187], v[26:29]
	v_mfma_f32_16x16x32_bf16 v[14:17], v[232:235], v[192:195], v[14:17]
	v_mfma_f32_16x16x32_bf16 v[10:13], v[240:243], v[192:195], v[10:13]
	v_mfma_f32_16x16x32_bf16 v[6:9], v[232:235], v[224:227], v[6:9]
	v_mfma_f32_16x16x32_bf16 v[2:5], v[240:243], v[224:227], v[2:5]
	s_add_i32 s13, s13, 2
	s_add_u32 s46, s46, 0x100
	s_addc_u32 s47, s47, 0
	s_add_u32 s1, s1, 0x100
	s_addc_u32 s12, s12, 0
	s_cmp_gt_u32 s13, 29
	s_barrier
	s_cbranch_scc0 .LBB0_788
	s_cmp_lg_u32 s62, 0
	s_cbranch_scc0 .LBB0_791
	s_lshl_b32 s1, s60, 8
	s_mov_b64 s[12:13], 0
	s_branch .LBB0_792
